# K-loops: removed the redundant second lgkmcnt(0) at the head of each MFMA block (already drained before the barrier)
# speedup vs baseline: 1.0092x; 1.0092x over previous
; #define PG8_STAGE(bufoff, gbase, voff) do { _Pragma("unroll") for (int _i = 0; _i < 2; ++_i) \
;         __builtin_amdgcn_global_load_lds((const unsigned*)((const char*)(gbase) + (voff)[_i]), (LAS unsigned*)(lds + (bufoff) + ldsw + _i * 8192), 16, 0, 0); } while (0)
; #define PG8_LDA(dst, b, h) do { _Pragma("unroll") for (int m = 0; m < 4; ++m) _Pragma("unroll") for (int k = 0; k < 2; ++k) dst[m][k] = *(const LAS bf16x8*)(lds + PG8_SA(b, h) + aoff + m * 2048 + k * 1024); } while (0)
; #define PG8_LDB(dst, b, h) do { _Pragma("unroll") for (int n = 0; n < 2; ++n) _Pragma("unroll") for (int k = 0; k < 2; ++k) dst[n][k] = *(const LAS bf16x8*)(lds + PG8_SB(b, h) + boff + n * 2048 + k * 1024); } while (0)
; #define PG8_MMA(ai, bj, At, Bt) do { __builtin_amdgcn_s_setprio(1); _Pragma("unroll") for (int m = 0; m < 4; ++m) _Pragma("unroll") for (int n = 0; n < 2; ++n) _Pragma("unroll") for (int k = 0; k < 2; ++k) \
;         acc[ai][bj][m][n] = __builtin_amdgcn_mfma_f32_16x16x32_bf16(Bt[n][k], At[m][k], acc[ai][bj][m][n], 0, 0, 0); __builtin_amdgcn_s_setprio(0); } while (0)
; #define PG8_WAIT_V(n) asm volatile("s_waitcnt vmcnt(" #n ")" ::: "memory")
; #define PG8_WAIT_L(n) asm volatile("s_waitcnt lgkmcnt(" #n ")" ::: "memory")
; #define PG8_BAR __builtin_amdgcn_s_barrier()
; #define PG8_SCHED __builtin_amdgcn_sched_barrier(0)
; template <class Epi, bool ALIGN_EPI>
; __device__ __forceinline__ void gemm_phase(LAS unsigned char* lds, const Gemm g, int G, int cid, const Epi& E) {
;     ...
;         for (int t = 0; t < nt; t += 2) {
;             const bool last = (t == nt - 2);
;             const char* a1 = cA + (size_t)(t + 1) * kA;
;             const char* a2 = last ? nA : cA + (size_t)(t + 2) * kA; const char* b2 = last ? nB : cB + (size_t)(t + 2) * kB;
;             const char* a3 = a2 + kA; const char* b3 = b2 + kB;
;             PG8_LDB(B0, 0, 0); PG8_LDB(B1, 0, 1); PG8_SCHED; PG8_LDA(At, 0, 0); PG8_STAGE(PG8_SA(1, 1), a1 + hA, voffA);
;             PG8_WAIT_V(8); PG8_WAIT_L(0); PG8_BAR; PG8_MMA(0, 0, At, B0); PG8_MMA(0, 1, At, B1); PG8_BAR; PG8_SCHED;
;             PG8_LDA(At, 0, 1); PG8_STAGE(PG8_SB(0, 0), b2, voffB); PG8_STAGE(PG8_SB(0, 1), b2 + hB, voffB); PG8_STAGE(PG8_SA(0, 0), a2, voffA);
;             PG8_WAIT_V(8); PG8_WAIT_L(0); PG8_BAR; PG8_MMA(1, 0, At, B0); PG8_MMA(1, 1, At, B1); PG8_BAR; PG8_SCHED;
.LBB0_169:
	s_add_u32 s44, s50, 0x100
	s_addc_u32 s45, s51, 0
	s_add_i32 s6, 0, 0x10000
	s_cmp_eq_u32 s79, 4
	s_cselect_b32 s55, s43, s45
	s_cselect_b32 s54, s42, s44
	s_cselect_b32 s53, s30, s78
	s_cselect_b32 s52, s76, s77
	s_add_i32 s86, 0, 0x14000
	v_add_u32_e32 v84, s6, v212
	v_add_u32_e32 v100, s86, v212
	ds_read_b128 v[68:71], v84
	ds_read_b128 v[76:79], v84 offset:1024
	ds_read_b128 v[80:83], v84 offset:2048
	ds_read_b128 v[84:87], v84 offset:3072
	ds_read_b128 v[88:91], v100
	ds_read_b128 v[92:95], v100 offset:1024
	ds_read_b128 v[96:99], v100 offset:2048
	ds_read_b128 v[100:103], v100 offset:3072
	v_lshl_add_u64 v[198:199], s[50:51], 0, v[184:185]
	s_add_i32 m0, s24, 0xc000
	ds_read_b128 v[164:167], v214
	ds_read_b128 v[168:171], v214 offset:1024
	ds_read_b128 v[172:175], v214 offset:2048
	ds_read_b128 v[176:179], v214 offset:3072
	ds_read_b128 v[188:191], v214 offset:4096
	ds_read_b128 v[206:209], v214 offset:5120
	ds_read_b128 v[216:219], v214 offset:6144
	ds_read_b128 v[220:223], v214 offset:7168
	global_load_lds_dwordx4 v[198:199], off
	v_lshl_add_u64 v[198:199], s[50:51], 0, v[186:187]
	s_add_i32 m0, s24, 0xe000
	s_nop 0
	global_load_lds_dwordx4 v[198:199], off
	s_waitcnt vmcnt(8)
	s_waitcnt lgkmcnt(0)
	s_barrier
	s_setprio 1
	v_mfma_f32_16x16x32_bf16 v[160:163], v[68:71], v[164:167], v[160:163]
	v_mfma_f32_16x16x32_bf16 v[156:159], v[80:83], v[164:167], v[156:159]
	v_mfma_f32_16x16x32_bf16 v[144:147], v[68:71], v[172:175], v[144:147]
	v_mfma_f32_16x16x32_bf16 v[140:143], v[80:83], v[172:175], v[140:143]
	v_mfma_f32_16x16x32_bf16 v[124:127], v[68:71], v[188:191], v[124:127]
	v_mfma_f32_16x16x32_bf16 v[120:123], v[80:83], v[188:191], v[120:123]
	v_mfma_f32_16x16x32_bf16 v[108:111], v[68:71], v[216:219], v[108:111]
	v_mfma_f32_16x16x32_bf16 v[104:107], v[80:83], v[216:219], v[104:107]
	v_mfma_f32_16x16x32_bf16 v[160:163], v[76:79], v[168:171], v[160:163]
	v_mfma_f32_16x16x32_bf16 v[156:159], v[84:87], v[168:171], v[156:159]
	v_mfma_f32_16x16x32_bf16 v[144:147], v[76:79], v[176:179], v[144:147]
	v_mfma_f32_16x16x32_bf16 v[140:143], v[84:87], v[176:179], v[140:143]
	v_mfma_f32_16x16x32_bf16 v[124:127], v[76:79], v[206:209], v[124:127]
	v_mfma_f32_16x16x32_bf16 v[120:123], v[84:87], v[206:209], v[120:123]
	v_mfma_f32_16x16x32_bf16 v[108:111], v[76:79], v[220:223], v[108:111]
	v_mfma_f32_16x16x32_bf16 v[104:107], v[84:87], v[220:223], v[104:107]
	s_setprio 0
	s_setprio 1
	v_mfma_f32_16x16x32_bf16 v[152:155], v[88:91], v[164:167], v[152:155]
	v_mfma_f32_16x16x32_bf16 v[148:151], v[96:99], v[164:167], v[148:151]
	v_mfma_f32_16x16x32_bf16 v[132:135], v[88:91], v[172:175], v[132:135]
	v_mfma_f32_16x16x32_bf16 v[128:131], v[96:99], v[172:175], v[128:131]
	v_mfma_f32_16x16x32_bf16 v[116:119], v[88:91], v[188:191], v[116:119]
	v_mfma_f32_16x16x32_bf16 v[112:115], v[96:99], v[188:191], v[112:115]
	v_mfma_f32_16x16x32_bf16 v[72:75], v[88:91], v[216:219], v[72:75]
	v_mfma_f32_16x16x32_bf16 v[64:67], v[96:99], v[216:219], v[64:67]
	v_mfma_f32_16x16x32_bf16 v[152:155], v[92:95], v[168:171], v[152:155]
	v_mfma_f32_16x16x32_bf16 v[148:151], v[100:103], v[168:171], v[148:151]
	v_mfma_f32_16x16x32_bf16 v[132:135], v[92:95], v[176:179], v[132:135]
	v_mfma_f32_16x16x32_bf16 v[128:131], v[100:103], v[176:179], v[128:131]
	v_mfma_f32_16x16x32_bf16 v[116:119], v[92:95], v[206:209], v[116:119]
	v_mfma_f32_16x16x32_bf16 v[112:115], v[100:103], v[206:209], v[112:115]
	v_mfma_f32_16x16x32_bf16 v[72:75], v[92:95], v[220:223], v[72:75]
	v_mfma_f32_16x16x32_bf16 v[64:67], v[100:103], v[220:223], v[64:67]
	s_setprio 0
	s_barrier
	s_add_i32 s6, s6, s23
	v_lshl_add_u64 v[198:199], s[52:53], 0, v[138:139]
	s_mov_b32 m0, s6
	ds_read_b128 v[164:167], v214 offset:16384
	ds_read_b128 v[168:171], v214 offset:17408
	ds_read_b128 v[172:175], v214 offset:18432
	ds_read_b128 v[176:179], v214 offset:19456
	ds_read_b128 v[188:191], v214 offset:20480
	ds_read_b128 v[206:209], v214 offset:21504
	ds_read_b128 v[216:219], v214 offset:22528
	ds_read_b128 v[220:223], v214 offset:23552
	global_load_lds_dwordx4 v[198:199], off
	s_add_i32 m0, s6, 0x2000
	s_add_u32 s6, s52, 0x2000
	v_lshl_add_u64 v[198:199], s[52:53], 0, v[136:137]
	s_addc_u32 s7, s53, 0
	s_add_i32 s50, s86, s23
	global_load_lds_dwordx4 v[198:199], off
	v_lshl_add_u64 v[198:199], s[6:7], 0, v[138:139]
	s_mov_b32 m0, s50
	v_lshl_add_u64 v[200:201], s[54:55], 0, v[180:181]
	global_load_lds_dwordx4 v[198:199], off
	v_lshl_add_u64 v[198:199], s[6:7], 0, v[136:137]
	s_add_i32 m0, s50, 0x2000
	s_nop 0
	global_load_lds_dwordx4 v[198:199], off
	v_lshl_add_u64 v[198:199], s[54:55], 0, v[182:183]
	s_mov_b32 m0, s24
	s_nop 0
	global_load_lds_dwordx4 v[198:199], off
	s_mov_b32 m0, s25
	s_nop 0
	global_load_lds_dwordx4 v[200:201], off
	s_waitcnt vmcnt(8)
	s_waitcnt lgkmcnt(0)
	s_barrier
; #define PG8_STAGE(bufoff, gbase, voff) do { _Pragma("unroll") for (int _i = 0; _i < 2; ++_i) \
;         __builtin_amdgcn_global_load_lds((const unsigned*)((const char*)(gbase) + (voff)[_i]), (LAS unsigned*)(lds + (bufoff) + ldsw + _i * 8192), 16, 0, 0); } while (0)
; #define PG8_LDA(dst, b, h) do { _Pragma("unroll") for (int m = 0; m < 4; ++m) _Pragma("unroll") for (int k = 0; k < 2; ++k) dst[m][k] = *(const LAS bf16x8*)(lds + PG8_SA(b, h) + aoff + m * 2048 + k * 1024); } while (0)
; #define PG8_LDB(dst, b, h) do { _Pragma("unroll") for (int n = 0; n < 2; ++n) _Pragma("unroll") for (int k = 0; k < 2; ++k) dst[n][k] = *(const LAS bf16x8*)(lds + PG8_SB(b, h) + boff + n * 2048 + k * 1024); } while (0)
; #define PG8_MMA(ai, bj, At, Bt) do { __builtin_amdgcn_s_setprio(1); _Pragma("unroll") for (int m = 0; m < 4; ++m) _Pragma("unroll") for (int n = 0; n < 2; ++n) _Pragma("unroll") for (int k = 0; k < 2; ++k) \
;         acc[ai][bj][m][n] = __builtin_amdgcn_mfma_f32_16x16x32_bf16(Bt[n][k], At[m][k], acc[ai][bj][m][n], 0, 0, 0); __builtin_amdgcn_s_setprio(0); } while (0)
; #define PG8_WAIT_V(n) asm volatile("s_waitcnt vmcnt(" #n ")" ::: "memory")
; #define PG8_WAIT_L(n) asm volatile("s_waitcnt lgkmcnt(" #n ")" ::: "memory")
; #define PG8_BAR __builtin_amdgcn_s_barrier()
; #define PG8_SCHED __builtin_amdgcn_sched_barrier(0)
; template <class Epi, bool ALIGN_EPI>
; __device__ __forceinline__ void gemm_phase(LAS unsigned char* lds, const Gemm g, int G, int cid, const Epi& E) {
;     ...
;             PG8_WAIT_V(8); PG8_WAIT_L(0); PG8_BAR; PG8_MMA(1, 0, At, B0); PG8_MMA(1, 1, At, B1); PG8_BAR; PG8_SCHED;
;             PG8_LDB(B0, 1, 0); PG8_LDB(B1, 1, 1); PG8_SCHED; PG8_LDA(At, 1, 0); PG8_STAGE(PG8_SA(0, 1), a2 + hA, voffA);
;             PG8_WAIT_V(8); PG8_WAIT_L(0); PG8_BAR; PG8_MMA(0, 0, At, B0); PG8_MMA(0, 1, At, B1); PG8_BAR; PG8_SCHED;
	s_setprio 1
	v_mfma_f32_16x16x32_bf16 v[60:63], v[68:71], v[164:167], v[60:63]
	v_mfma_f32_16x16x32_bf16 v[56:59], v[80:83], v[164:167], v[56:59]
	v_mfma_f32_16x16x32_bf16 v[44:47], v[68:71], v[172:175], v[44:47]
	v_mfma_f32_16x16x32_bf16 v[40:43], v[80:83], v[172:175], v[40:43]
	v_mfma_f32_16x16x32_bf16 v[28:31], v[68:71], v[188:191], v[28:31]
	v_mfma_f32_16x16x32_bf16 v[24:27], v[80:83], v[188:191], v[24:27]
	v_mfma_f32_16x16x32_bf16 v[12:15], v[68:71], v[216:219], v[12:15]
	v_mfma_f32_16x16x32_bf16 v[8:11], v[80:83], v[216:219], v[8:11]
	v_mfma_f32_16x16x32_bf16 v[60:63], v[76:79], v[168:171], v[60:63]
	v_mfma_f32_16x16x32_bf16 v[56:59], v[84:87], v[168:171], v[56:59]
	v_mfma_f32_16x16x32_bf16 v[44:47], v[76:79], v[176:179], v[44:47]
	v_mfma_f32_16x16x32_bf16 v[40:43], v[84:87], v[176:179], v[40:43]
	v_mfma_f32_16x16x32_bf16 v[28:31], v[76:79], v[206:209], v[28:31]
	v_mfma_f32_16x16x32_bf16 v[24:27], v[84:87], v[206:209], v[24:27]
	v_mfma_f32_16x16x32_bf16 v[12:15], v[76:79], v[220:223], v[12:15]
	v_mfma_f32_16x16x32_bf16 v[8:11], v[84:87], v[220:223], v[8:11]
	s_setprio 0
	s_setprio 1
	v_mfma_f32_16x16x32_bf16 v[52:55], v[88:91], v[164:167], v[52:55]
	v_mfma_f32_16x16x32_bf16 v[48:51], v[96:99], v[164:167], v[48:51]
	v_mfma_f32_16x16x32_bf16 v[36:39], v[88:91], v[172:175], v[36:39]
	v_mfma_f32_16x16x32_bf16 v[32:35], v[96:99], v[172:175], v[32:35]
	v_mfma_f32_16x16x32_bf16 v[20:23], v[88:91], v[188:191], v[20:23]
	v_mfma_f32_16x16x32_bf16 v[16:19], v[96:99], v[188:191], v[16:19]
	v_mfma_f32_16x16x32_bf16 v[4:7], v[88:91], v[216:219], v[4:7]
	v_mfma_f32_16x16x32_bf16 v[0:3], v[96:99], v[216:219], v[0:3]
	v_mfma_f32_16x16x32_bf16 v[52:55], v[92:95], v[168:171], v[52:55]
	v_mfma_f32_16x16x32_bf16 v[48:51], v[100:103], v[168:171], v[48:51]
	v_mfma_f32_16x16x32_bf16 v[36:39], v[92:95], v[176:179], v[36:39]
	v_mfma_f32_16x16x32_bf16 v[32:35], v[100:103], v[176:179], v[32:35]
	v_mfma_f32_16x16x32_bf16 v[20:23], v[92:95], v[206:209], v[20:23]
	v_mfma_f32_16x16x32_bf16 v[16:19], v[100:103], v[206:209], v[16:19]
	v_mfma_f32_16x16x32_bf16 v[4:7], v[92:95], v[220:223], v[4:7]
	v_mfma_f32_16x16x32_bf16 v[0:3], v[100:103], v[220:223], v[0:3]
	s_setprio 0
	s_barrier
	s_add_i32 s50, 0, 0x18000
	s_add_i32 s51, 0, 0x1c000
	v_add_u32_e32 v84, s50, v212
	v_add_u32_e32 v100, s51, v212
	ds_read_b128 v[68:71], v84
	ds_read_b128 v[76:79], v84 offset:1024
	ds_read_b128 v[80:83], v84 offset:2048
	ds_read_b128 v[84:87], v84 offset:3072
	ds_read_b128 v[88:91], v100
	ds_read_b128 v[92:95], v100 offset:1024
	ds_read_b128 v[96:99], v100 offset:2048
	ds_read_b128 v[100:103], v100 offset:3072
	s_add_u32 s6, s54, 0x84000
	s_addc_u32 s7, s55, 0
	s_mov_b32 m0, s56
	v_lshl_add_u64 v[210:211], s[6:7], 0, v[182:183]
	ds_read_b128 v[164:167], v214 offset:32768
	ds_read_b128 v[168:171], v214 offset:33792
	ds_read_b128 v[172:175], v214 offset:34816
	ds_read_b128 v[176:179], v214 offset:35840
	ds_read_b128 v[188:191], v214 offset:36864
	ds_read_b128 v[206:209], v214 offset:37888
	ds_read_b128 v[216:219], v214 offset:38912
	ds_read_b128 v[220:223], v214 offset:39936
	global_load_lds_dwordx4 v[210:211], off
	v_lshl_add_u64 v[210:211], s[6:7], 0, v[180:181]
	s_mov_b32 m0, s57
	s_nop 0
	global_load_lds_dwordx4 v[210:211], off
	s_waitcnt vmcnt(8)
	s_waitcnt lgkmcnt(0)
	s_barrier
	s_setprio 1
	v_mfma_f32_16x16x32_bf16 v[160:163], v[68:71], v[164:167], v[160:163]
	v_mfma_f32_16x16x32_bf16 v[156:159], v[80:83], v[164:167], v[156:159]
	v_mfma_f32_16x16x32_bf16 v[144:147], v[68:71], v[172:175], v[144:147]
	v_mfma_f32_16x16x32_bf16 v[140:143], v[80:83], v[172:175], v[140:143]
	v_mfma_f32_16x16x32_bf16 v[124:127], v[68:71], v[188:191], v[124:127]
	v_mfma_f32_16x16x32_bf16 v[120:123], v[80:83], v[188:191], v[120:123]
	v_mfma_f32_16x16x32_bf16 v[108:111], v[68:71], v[216:219], v[108:111]
	v_mfma_f32_16x16x32_bf16 v[104:107], v[80:83], v[216:219], v[104:107]
	v_mfma_f32_16x16x32_bf16 v[160:163], v[76:79], v[168:171], v[160:163]
	v_mfma_f32_16x16x32_bf16 v[156:159], v[84:87], v[168:171], v[156:159]
	v_mfma_f32_16x16x32_bf16 v[144:147], v[76:79], v[176:179], v[144:147]
	v_mfma_f32_16x16x32_bf16 v[140:143], v[84:87], v[176:179], v[140:143]
	v_mfma_f32_16x16x32_bf16 v[124:127], v[76:79], v[206:209], v[124:127]
	v_mfma_f32_16x16x32_bf16 v[120:123], v[84:87], v[206:209], v[120:123]
	v_mfma_f32_16x16x32_bf16 v[108:111], v[76:79], v[220:223], v[108:111]
	v_mfma_f32_16x16x32_bf16 v[104:107], v[84:87], v[220:223], v[104:107]
	s_setprio 0
	s_setprio 1
	v_mfma_f32_16x16x32_bf16 v[152:155], v[88:91], v[164:167], v[152:155]
	v_mfma_f32_16x16x32_bf16 v[148:151], v[96:99], v[164:167], v[148:151]
	v_mfma_f32_16x16x32_bf16 v[132:135], v[88:91], v[172:175], v[132:135]
	v_mfma_f32_16x16x32_bf16 v[128:131], v[96:99], v[172:175], v[128:131]
	v_mfma_f32_16x16x32_bf16 v[116:119], v[88:91], v[188:191], v[116:119]
	v_mfma_f32_16x16x32_bf16 v[112:115], v[96:99], v[188:191], v[112:115]
	v_mfma_f32_16x16x32_bf16 v[72:75], v[88:91], v[216:219], v[72:75]
	v_mfma_f32_16x16x32_bf16 v[64:67], v[96:99], v[216:219], v[64:67]
	v_mfma_f32_16x16x32_bf16 v[152:155], v[92:95], v[168:171], v[152:155]
	v_mfma_f32_16x16x32_bf16 v[148:151], v[100:103], v[168:171], v[148:151]
	v_mfma_f32_16x16x32_bf16 v[132:135], v[92:95], v[176:179], v[132:135]
	v_mfma_f32_16x16x32_bf16 v[128:131], v[100:103], v[176:179], v[128:131]
	v_mfma_f32_16x16x32_bf16 v[116:119], v[92:95], v[206:209], v[116:119]
	v_mfma_f32_16x16x32_bf16 v[112:115], v[100:103], v[206:209], v[112:115]
	v_mfma_f32_16x16x32_bf16 v[72:75], v[92:95], v[220:223], v[72:75]
	v_mfma_f32_16x16x32_bf16 v[64:67], v[100:103], v[220:223], v[64:67]
	s_setprio 0
	s_barrier
; #define PG8_STAGE(bufoff, gbase, voff) do { _Pragma("unroll") for (int _i = 0; _i < 2; ++_i) \
;         __builtin_amdgcn_global_load_lds((const unsigned*)((const char*)(gbase) + (voff)[_i]), (LAS unsigned*)(lds + (bufoff) + ldsw + _i * 8192), 16, 0, 0); } while (0)
; #define PG8_LDA(dst, b, h) do { _Pragma("unroll") for (int m = 0; m < 4; ++m) _Pragma("unroll") for (int k = 0; k < 2; ++k) dst[m][k] = *(const LAS bf16x8*)(lds + PG8_SA(b, h) + aoff + m * 2048 + k * 1024); } while (0)
; #define PG8_MMA(ai, bj, At, Bt) do { __builtin_amdgcn_s_setprio(1); _Pragma("unroll") for (int m = 0; m < 4; ++m) _Pragma("unroll") for (int n = 0; n < 2; ++n) _Pragma("unroll") for (int k = 0; k < 2; ++k) \
;         acc[ai][bj][m][n] = __builtin_amdgcn_mfma_f32_16x16x32_bf16(Bt[n][k], At[m][k], acc[ai][bj][m][n], 0, 0, 0); __builtin_amdgcn_s_setprio(0); } while (0)
; #define PG8_WAIT_V(n) asm volatile("s_waitcnt vmcnt(" #n ")" ::: "memory")
; #define PG8_WAIT_L(n) asm volatile("s_waitcnt lgkmcnt(" #n ")" ::: "memory")
; #define PG8_BAR __builtin_amdgcn_s_barrier()
; #define PG8_SCHED __builtin_amdgcn_sched_barrier(0)
; template <class Epi, bool ALIGN_EPI>
; __device__ __forceinline__ void gemm_phase(LAS unsigned char* lds, const Gemm g, int G, int cid, const Epi& E) {
;     ...
;         for (int t = 0; t < nt; t += 2) {
;     ...
;             PG8_LDA(At, 1, 1); PG8_STAGE(PG8_SB(1, 0), b3, voffB); PG8_STAGE(PG8_SB(1, 1), b3 + hB, voffB); PG8_STAGE(PG8_SA(1, 0), a3, voffA);
;             PG8_WAIT_V(8); PG8_WAIT_L(0); PG8_BAR; PG8_MMA(1, 0, At, B0); PG8_MMA(1, 1, At, B1); PG8_BAR; PG8_SCHED;
	s_add_u32 s6, s52, 0x10000
	s_addc_u32 s7, s53, 0
	s_add_i32 s50, s50, s23
	v_lshl_add_u64 v[210:211], s[6:7], 0, v[138:139]
	s_mov_b32 m0, s50
	ds_read_b128 v[164:167], v214 offset:49152
	ds_read_b128 v[168:171], v214 offset:50176
	ds_read_b128 v[172:175], v214 offset:51200
	ds_read_b128 v[176:179], v214 offset:52224
	ds_read_b128 v[188:191], v214 offset:53248
	ds_read_b128 v[206:209], v214 offset:54272
	ds_read_b128 v[216:219], v214 offset:55296
	ds_read_b128 v[220:223], v214 offset:56320
	global_load_lds_dwordx4 v[210:211], off
	s_add_i32 m0, s50, 0x2000
	v_lshl_add_u64 v[210:211], s[6:7], 0, v[136:137]
	s_add_u32 s6, s52, 0x12000
	s_addc_u32 s7, s53, 0
	s_add_i32 s50, s51, s23
	global_load_lds_dwordx4 v[210:211], off
	v_lshl_add_u64 v[210:211], s[6:7], 0, v[138:139]
	s_mov_b32 m0, s50
	v_lshl_add_u64 v[198:199], v[198:199], 0, s[36:37]
	global_load_lds_dwordx4 v[210:211], off
	v_lshl_add_u64 v[210:211], s[6:7], 0, v[136:137]
	s_add_i32 m0, s50, 0x2000
	s_nop 0
	global_load_lds_dwordx4 v[210:211], off
	s_mov_b32 m0, s59
	s_nop 0
	global_load_lds_dwordx4 v[198:199], off
	v_lshl_add_u64 v[198:199], v[200:201], 0, s[36:37]
	s_mov_b32 m0, s72
	s_nop 0
	global_load_lds_dwordx4 v[198:199], off
	s_waitcnt vmcnt(8)
	s_waitcnt lgkmcnt(0)
	s_barrier
	s_setprio 1
	v_mfma_f32_16x16x32_bf16 v[60:63], v[68:71], v[164:167], v[60:63]
	v_mfma_f32_16x16x32_bf16 v[56:59], v[80:83], v[164:167], v[56:59]
	v_mfma_f32_16x16x32_bf16 v[44:47], v[68:71], v[172:175], v[44:47]
	v_mfma_f32_16x16x32_bf16 v[40:43], v[80:83], v[172:175], v[40:43]
	v_mfma_f32_16x16x32_bf16 v[28:31], v[68:71], v[188:191], v[28:31]
	v_mfma_f32_16x16x32_bf16 v[24:27], v[80:83], v[188:191], v[24:27]
	v_mfma_f32_16x16x32_bf16 v[12:15], v[68:71], v[216:219], v[12:15]
	v_mfma_f32_16x16x32_bf16 v[8:11], v[80:83], v[216:219], v[8:11]
	v_mfma_f32_16x16x32_bf16 v[60:63], v[76:79], v[168:171], v[60:63]
	v_mfma_f32_16x16x32_bf16 v[56:59], v[84:87], v[168:171], v[56:59]
	v_mfma_f32_16x16x32_bf16 v[44:47], v[76:79], v[176:179], v[44:47]
	v_mfma_f32_16x16x32_bf16 v[40:43], v[84:87], v[176:179], v[40:43]
	v_mfma_f32_16x16x32_bf16 v[28:31], v[76:79], v[206:209], v[28:31]
	v_mfma_f32_16x16x32_bf16 v[24:27], v[84:87], v[206:209], v[24:27]
	v_mfma_f32_16x16x32_bf16 v[12:15], v[76:79], v[220:223], v[12:15]
	v_mfma_f32_16x16x32_bf16 v[8:11], v[84:87], v[220:223], v[8:11]
	s_setprio 0
	s_setprio 1
	v_mfma_f32_16x16x32_bf16 v[52:55], v[88:91], v[164:167], v[52:55]
	v_mfma_f32_16x16x32_bf16 v[48:51], v[96:99], v[164:167], v[48:51]
	v_mfma_f32_16x16x32_bf16 v[36:39], v[88:91], v[172:175], v[36:39]
	v_mfma_f32_16x16x32_bf16 v[32:35], v[96:99], v[172:175], v[32:35]
	v_mfma_f32_16x16x32_bf16 v[20:23], v[88:91], v[188:191], v[20:23]
	v_mfma_f32_16x16x32_bf16 v[16:19], v[96:99], v[188:191], v[16:19]
	v_mfma_f32_16x16x32_bf16 v[4:7], v[88:91], v[216:219], v[4:7]
	v_mfma_f32_16x16x32_bf16 v[0:3], v[96:99], v[216:219], v[0:3]
	v_mfma_f32_16x16x32_bf16 v[52:55], v[92:95], v[168:171], v[52:55]
	v_mfma_f32_16x16x32_bf16 v[48:51], v[100:103], v[168:171], v[48:51]
	v_mfma_f32_16x16x32_bf16 v[36:39], v[92:95], v[176:179], v[36:39]
	v_mfma_f32_16x16x32_bf16 v[32:35], v[100:103], v[176:179], v[32:35]
	v_mfma_f32_16x16x32_bf16 v[20:23], v[92:95], v[206:209], v[20:23]
	v_mfma_f32_16x16x32_bf16 v[16:19], v[100:103], v[206:209], v[16:19]
	v_mfma_f32_16x16x32_bf16 v[4:7], v[92:95], v[220:223], v[4:7]
	v_mfma_f32_16x16x32_bf16 v[0:3], v[100:103], v[220:223], v[0:3]
	s_setprio 0
	s_barrier
	s_add_i32 s79, s79, 2
	s_add_u32 s77, s77, 0x20000
	s_addc_u32 s78, s78, 0
	s_cmp_lt_u32 s79, 6
	s_mov_b64 s[50:51], s[44:45]
	s_cbranch_scc1 .LBB0_169
; __device__ __forceinline__ unsigned cvt_pk_bf16(float lo, float hi) { unsigned r; asm volatile("v_cvt_pk_bf16_f32 %0, %1, %2" : "=v"(r) : "v"(lo), "v"(hi)); return r; }
;     __device__ __forceinline__ void operator()(const f32x4 (&acc)[2][2][4][2], const Unit& u, int wr, int wc, int fr, int fq, const LAS float*) const {
;     ...
;         for (int am = 0; am < NB; ++am) { const int ai = am / (NB / 2), m0 = (am % (NB / 2)) * MB;
;             f32x4 xo[4][2][2];
; #pragma unroll
;             for (int m = m0; m < m0 + MB; ++m) { const float* xr = Xs + (size_t)(row0 + ai * HALF + m * 16) * DM + col0;
; #pragma unroll
;                 for (int bj = 0; bj < 2; ++bj) { xo[m][bj][0] = *(const f32x4*)(xr + bj * HALF); xo[m][bj][1] = *(const f32x4*)(xr + bj * HALF + 4); } }
; #pragma unroll
;             for (int m = m0; m < m0 + MB; ++m) { const int row = row0 + ai * HALF + m * 16; float ss = 0.f;
;                 float* xr = X + (size_t)row * DM + col0; bf16_t* xb = XB + (size_t)row * ALD + col0;
; #pragma unroll
;                 for (int bj = 0; bj < 2; ++bj) { f32x4 x0 = xo[m][bj][0], x1 = xo[m][bj][1];
;                     if (HB) { x0 += (acc[ai][bj][m][0] + bv[bj][0]) * sv[bj][0]; x1 += (acc[ai][bj][m][1] + bv[bj][1]) * sv[bj][1]; } else { x0 += acc[ai][bj][m][0]; x1 += acc[ai][bj][m][1]; }
;                     *(f32x4*)(xr + bj * HALF) = x0; *(f32x4*)(xr + bj * HALF + 4) = x1;
;                     ss += (x0[0] * x0[0] + x0[1] * x0[1]) + (x0[2] * x0[2] + x0[3] * x0[3]) + (x1[0] * x1[0] + x1[1] * x1[1]) + (x1[2] * x1[2] + x1[3] * x1[3]);
;                     u32x4 w; w.x = cvt_pk_bf16(x0[0], x0[1]); w.y = cvt_pk_bf16(x0[2], x0[3]); w.z = cvt_pk_bf16(x1[0], x1[1]); w.w = cvt_pk_bf16(x1[2], x1[3]);
;                     if (feeds) *(u32x4*)(xb + bj * HALF) = w; }
;                 ss += __shfl_xor(ss, 16); ss += __shfl_xor(ss, 32);
;                 if (fq == 0 && feeds) part[(size_t)row * NPART + u.pn * 4 + wc] = ss; }
	v_lshl_or_b32 v188, s12, 8, v213
	v_ashrrev_i32_e32 v189, 31, v188
	v_lshl_add_u32 v190, s13, 8, v197
	v_lshlrev_b64 v[198:199], 2, v[188:189]
	v_ashrrev_i32_e32 v191, 31, v190
	v_lshl_add_u64 v[206:207], s[82:83], 0, v[198:199]
	v_lshlrev_b64 v[200:201], 13, v[190:191]
	v_lshl_add_u64 v[68:69], s[28:29], 0, v[198:199]
	v_lshl_add_u64 v[80:81], s[46:47], 0, v[198:199]
	v_lshl_add_u64 v[164:165], v[206:207], 0, v[200:201]
	global_load_dwordx4 v[92:95], v[68:69], off offset:16
	global_load_dwordx4 v[100:103], v[68:69], off
	global_load_dwordx4 v[88:91], v[80:81], off offset:16
	global_load_dwordx4 v[96:99], v[80:81], off
	global_load_dwordx4 v[76:79], v[68:69], off offset:528
	global_load_dwordx4 v[84:87], v[68:69], off offset:512
	s_nop 0
	global_load_dwordx4 v[68:71], v[80:81], off offset:528
	s_nop 0
	global_load_dwordx4 v[80:83], v[80:81], off offset:512
	s_nop 0
	global_load_dwordx4 v[216:219], v[164:165], off offset:16
	global_load_dwordx4 v[220:223], v[164:165], off
	global_load_dwordx4 v[224:227], v[164:165], off offset:528
	global_load_dwordx4 v[228:231], v[164:165], off offset:512
	v_or_b32_e32 v208, 16, v190
	v_ashrrev_i32_e32 v209, 31, v208
	v_lshlrev_b64 v[210:211], 13, v[208:209]
	v_lshl_add_u64 v[168:169], v[206:207], 0, v[210:211]
	global_load_dwordx4 v[172:175], v[168:169], off offset:16
	global_load_dwordx4 v[176:179], v[168:169], off
	global_load_dwordx4 v[164:167], v[168:169], off offset:528
	s_nop 0
	global_load_dwordx4 v[168:171], v[168:169], off offset:512
	v_lshl_add_u64 v[200:201], s[82:83], 0, v[200:201]
	v_lshl_add_u64 v[198:199], v[200:201], 0, v[198:199]
	v_mov_b64_e32 v[200:201], s[4:5]
	v_mad_i64_i32 v[200:201], s[6:7], v190, s66, v[200:201]
	v_lshl_add_u64 v[200:201], v[188:189], 1, v[200:201]
	s_lshl_b32 s44, s12, 2
	s_ashr_i32 s45, s44, 31
	s_waitcnt vmcnt(0)
	v_pk_add_f32 v[156:157], v[156:157], v[92:93]
	v_pk_add_f32 v[162:163], v[162:163], v[102:103]
	v_pk_add_f32 v[160:161], v[160:161], v[100:101]
	v_pk_add_f32 v[158:159], v[158:159], v[94:95]
	v_pk_add_f32 v[148:149], v[148:149], v[76:77]
	v_pk_fma_f32 v[156:157], v[88:89], v[156:157], v[216:217]
	v_pk_fma_f32 v[162:163], v[98:99], v[162:163], v[222:223]
	v_pk_fma_f32 v[160:161], v[96:97], v[160:161], v[220:221]
	v_mul_f32_e32 v216, v163, v163
	v_mul_f32_e32 v215, v161, v161
	v_fmac_f32_e32 v215, v160, v160
	v_fmac_f32_e32 v216, v162, v162
	v_pk_add_f32 v[154:155], v[154:155], v[86:87]
	v_pk_add_f32 v[152:153], v[152:153], v[84:85]
	v_add_f32_e32 v215, v215, v216
	v_mul_f32_e32 v216, v157, v157
	v_pk_fma_f32 v[154:155], v[82:83], v[154:155], v[230:231]
	v_pk_fma_f32 v[152:153], v[80:81], v[152:153], v[228:229]
	v_pk_fma_f32 v[158:159], v[90:91], v[158:159], v[218:219]
	global_store_dwordx4 v[198:199], v[160:163], off
	global_store_dwordx4 v[198:199], v[156:159], off offset:16
	v_fmac_f32_e32 v216, v156, v156
	v_cvt_pk_bf16_f32 v160, v160, v161
	v_cvt_pk_bf16_f32 v161, v162, v163
	v_cvt_pk_bf16_f32 v162, v156, v157
	v_pk_fma_f32 v[148:149], v[68:69], v[148:149], v[224:225]
	v_mul_f32_e32 v156, v153, v153
	v_mul_f32_e32 v157, v155, v155
	v_fmac_f32_e32 v156, v152, v152
	v_fmac_f32_e32 v157, v154, v154
	v_pk_add_f32 v[150:151], v[150:151], v[78:79]
	v_add_f32_e32 v156, v156, v157
	v_mul_f32_e32 v157, v149, v149
	v_cvt_pk_bf16_f32 v163, v158, v159
	global_store_dwordx4 v[200:201], v[160:163], off
	v_pk_fma_f32 v[150:151], v[70:71], v[150:151], v[226:227]
	global_store_dwordx4 v[198:199], v[152:155], off offset:512
	global_store_dwordx4 v[198:199], v[148:151], off offset:528
	v_fmac_f32_e32 v157, v148, v148
	v_cvt_pk_bf16_f32 v152, v152, v153
	v_cvt_pk_bf16_f32 v153, v154, v155
	v_cvt_pk_bf16_f32 v154, v148, v149
	v_add_f32_e32 v215, v215, v216
	v_and_b32_e32 v149, 64, v239
	v_mul_f32_e32 v216, v159, v159
	v_add_f32_e32 v156, v156, v157
	v_mul_f32_e32 v157, v151, v151
	v_xor_b32_e32 v148, 16, v239
	v_add_u32_e32 v149, 64, v149
	v_fmac_f32_e32 v216, v158, v158
	v_fmac_f32_e32 v157, v150, v150
	v_cmp_lt_i32_e32 vcc, v148, v149
	v_add_f32_e32 v215, v216, v215
	v_add_f32_e32 v156, v157, v156
	v_cndmask_b32_e32 v148, v239, v148, vcc
	v_add_f32_e32 v156, v215, v156
	v_cvt_pk_bf16_f32 v155, v150, v151
	global_store_dwordx4 v[200:201], v[152:155], off offset:256
	v_xor_b32_e32 v150, 32, v239
	v_cmp_lt_i32_e32 vcc, v150, v149
	v_lshlrev_b32_e32 v154, 2, v148
	ds_bpermute_b32 v148, v154, v156
	v_cndmask_b32_e32 v149, v239, v150, vcc
	v_lshlrev_b32_e32 v155, 2, v149
	s_waitcnt lgkmcnt(0)
	v_add_f32_e32 v148, v156, v148
	ds_bpermute_b32 v149, v155, v148
	s_and_saveexec_b64 s[50:51], s[38:39]
	s_cbranch_execz .LBB0_172
	v_lshlrev_b64 v[150:151], 7, v[190:191]
	v_lshl_add_u64 v[150:151], s[94:95], 0, v[150:151]
	v_lshl_add_u64 v[150:151], s[44:45], 2, v[150:151]
	s_lshl_b32 s30, s58, 2
	v_lshl_add_u64 v[150:151], v[150:151], 0, s[30:31]
	s_waitcnt lgkmcnt(0)
	v_add_f32_e32 v148, v148, v149
	global_store_dword v[150:151], v148, off

; #define PG8_STAGE(bufoff, gbase, voff) do { _Pragma("unroll") for (int _i = 0; _i < 2; ++_i) \
;         __builtin_amdgcn_global_load_lds((const unsigned*)((const char*)(gbase) + (voff)[_i]), (LAS unsigned*)(lds + (bufoff) + ldsw + _i * 8192), 16, 0, 0); } while (0)
; #define PG8_LDA(dst, b, h) do { _Pragma("unroll") for (int m = 0; m < 4; ++m) _Pragma("unroll") for (int k = 0; k < 2; ++k) dst[m][k] = *(const LAS bf16x8*)(lds + PG8_SA(b, h) + aoff + m * 2048 + k * 1024); } while (0)
; #define PG8_LDB(dst, b, h) do { _Pragma("unroll") for (int n = 0; n < 2; ++n) _Pragma("unroll") for (int k = 0; k < 2; ++k) dst[n][k] = *(const LAS bf16x8*)(lds + PG8_SB(b, h) + boff + n * 2048 + k * 1024); } while (0)
; #define PG8_MMA(ai, bj, At, Bt) do { __builtin_amdgcn_s_setprio(1); _Pragma("unroll") for (int m = 0; m < 4; ++m) _Pragma("unroll") for (int n = 0; n < 2; ++n) _Pragma("unroll") for (int k = 0; k < 2; ++k) \
;         acc[ai][bj][m][n] = __builtin_amdgcn_mfma_f32_16x16x32_bf16(Bt[n][k], At[m][k], acc[ai][bj][m][n], 0, 0, 0); __builtin_amdgcn_s_setprio(0); } while (0)
; #define PG8_WAIT_V(n) asm volatile("s_waitcnt vmcnt(" #n ")" ::: "memory")
; #define PG8_WAIT_L(n) asm volatile("s_waitcnt lgkmcnt(" #n ")" ::: "memory")
; #define PG8_BAR __builtin_amdgcn_s_barrier()
; #define PG8_SCHED __builtin_amdgcn_sched_barrier(0)
; template <class Epi, bool ALIGN_EPI>
; __device__ __forceinline__ void gemm_phase(LAS unsigned char* lds, const Gemm g, int G, int cid, const Epi& E) {
;     ...
;             PG8_LDB(B0, 0, 0); PG8_LDB(B1, 0, 1); PG8_SCHED; PG8_LDA(At, 0, 0); PG8_STAGE(PG8_SA(1, 1), a1 + hA, voffA);
;             PG8_WAIT_V(8); PG8_WAIT_L(0); PG8_BAR; PG8_MMA(0, 0, At, B0); PG8_MMA(0, 1, At, B1); PG8_BAR; PG8_SCHED;
;             PG8_LDA(At, 0, 1); PG8_STAGE(PG8_SB(0, 0), b2, voffB); PG8_STAGE(PG8_SB(0, 1), b2 + hB, voffB); PG8_STAGE(PG8_SA(0, 0), a2, voffA);
;             PG8_WAIT_V(8); PG8_WAIT_L(0); PG8_BAR; PG8_MMA(1, 0, At, B0); PG8_MMA(1, 1, At, B1); PG8_BAR; PG8_SCHED;
.LBB0_266:
	s_add_u32 s74, s72, 0x100
	s_addc_u32 s75, s73, 0
	s_and_b64 s[58:59], exec, s[58:59]
	s_cselect_b32 s59, s49, s75
	s_cselect_b32 s58, s48, s74
	s_add_i32 s6, 0, 0x10000
	s_add_i32 s7, 0, 0x14000
	v_add_u32_e32 v108, s6, v190
	v_add_u32_e32 v132, s7, v190
	ds_read_b128 v[88:91], v108
	ds_read_b128 v[100:103], v108 offset:1024
	ds_read_b128 v[104:107], v108 offset:2048
	ds_read_b128 v[108:111], v108 offset:3072
	ds_read_b128 v[112:115], v132
	ds_read_b128 v[120:123], v132 offset:1024
	ds_read_b128 v[124:127], v132 offset:2048
	ds_read_b128 v[132:135], v132 offset:3072
	v_lshl_add_u64 v[198:199], s[72:73], 0, v[178:179]
	s_add_i32 m0, s23, 0xc000
	ds_read_b128 v[164:167], v222
	ds_read_b128 v[168:171], v222 offset:1024
	ds_read_b128 v[182:185], v222 offset:2048
	ds_read_b128 v[224:227], v222 offset:3072
	ds_read_b128 v[228:231], v222 offset:4096
	ds_read_b128 v[232:235], v222 offset:5120
	ds_read_b128 v[244:247], v222 offset:6144
	ds_read_b128 v[248:251], v222 offset:7168
	global_load_lds_dwordx4 v[198:199], off
	v_lshl_add_u64 v[198:199], s[72:73], 0, v[180:181]
	s_add_i32 m0, s23, 0xe000
	s_nop 0
	global_load_lds_dwordx4 v[198:199], off
	s_waitcnt vmcnt(8)
	s_waitcnt lgkmcnt(0)
	s_barrier
	s_setprio 1
	v_mfma_f32_16x16x32_bf16 v[160:163], v[88:91], v[164:167], v[160:163]
	v_mfma_f32_16x16x32_bf16 v[156:159], v[104:107], v[164:167], v[156:159]
	v_mfma_f32_16x16x32_bf16 v[144:147], v[88:91], v[182:185], v[144:147]
	v_mfma_f32_16x16x32_bf16 v[140:143], v[104:107], v[182:185], v[140:143]
	v_mfma_f32_16x16x32_bf16 v[96:99], v[88:91], v[228:231], v[96:99]
	v_mfma_f32_16x16x32_bf16 v[92:95], v[104:107], v[228:231], v[92:95]
	v_mfma_f32_16x16x32_bf16 v[76:79], v[88:91], v[244:247], v[76:79]
	v_mfma_f32_16x16x32_bf16 v[72:75], v[104:107], v[244:247], v[72:75]
	v_mfma_f32_16x16x32_bf16 v[160:163], v[100:103], v[168:171], v[160:163]
	v_mfma_f32_16x16x32_bf16 v[156:159], v[108:111], v[168:171], v[156:159]
	v_mfma_f32_16x16x32_bf16 v[144:147], v[100:103], v[224:227], v[144:147]
	v_mfma_f32_16x16x32_bf16 v[140:143], v[108:111], v[224:227], v[140:143]
	v_mfma_f32_16x16x32_bf16 v[96:99], v[100:103], v[232:235], v[96:99]
	v_mfma_f32_16x16x32_bf16 v[92:95], v[108:111], v[232:235], v[92:95]
	v_mfma_f32_16x16x32_bf16 v[76:79], v[100:103], v[248:251], v[76:79]
	v_mfma_f32_16x16x32_bf16 v[72:75], v[108:111], v[248:251], v[72:75]
	s_setprio 0
	s_setprio 1
	v_mfma_f32_16x16x32_bf16 v[152:155], v[112:115], v[164:167], v[152:155]
	v_mfma_f32_16x16x32_bf16 v[148:151], v[124:127], v[164:167], v[148:151]
	v_mfma_f32_16x16x32_bf16 v[128:131], v[112:115], v[182:185], v[128:131]
	v_mfma_f32_16x16x32_bf16 v[116:119], v[124:127], v[182:185], v[116:119]
	v_mfma_f32_16x16x32_bf16 v[84:87], v[112:115], v[228:231], v[84:87]
	v_mfma_f32_16x16x32_bf16 v[80:83], v[124:127], v[228:231], v[80:83]
	v_mfma_f32_16x16x32_bf16 v[68:71], v[112:115], v[244:247], v[68:71]
	v_mfma_f32_16x16x32_bf16 v[64:67], v[124:127], v[244:247], v[64:67]
	v_mfma_f32_16x16x32_bf16 v[152:155], v[120:123], v[168:171], v[152:155]
	v_mfma_f32_16x16x32_bf16 v[148:151], v[132:135], v[168:171], v[148:151]
	v_mfma_f32_16x16x32_bf16 v[128:131], v[120:123], v[224:227], v[128:131]
	v_mfma_f32_16x16x32_bf16 v[116:119], v[132:135], v[224:227], v[116:119]
	v_mfma_f32_16x16x32_bf16 v[84:87], v[120:123], v[232:235], v[84:87]
	v_mfma_f32_16x16x32_bf16 v[80:83], v[132:135], v[232:235], v[80:83]
	v_mfma_f32_16x16x32_bf16 v[68:71], v[120:123], v[248:251], v[68:71]
	v_mfma_f32_16x16x32_bf16 v[64:67], v[132:135], v[248:251], v[64:67]
	s_setprio 0
	s_barrier
	s_add_i32 s6, s6, s0
	v_lshl_add_u64 v[198:199], s[56:57], 0, v[172:173]
	s_mov_b32 m0, s6
	ds_read_b128 v[164:167], v222 offset:16384
	ds_read_b128 v[168:171], v222 offset:17408
	ds_read_b128 v[182:185], v222 offset:18432
	ds_read_b128 v[224:227], v222 offset:19456
	ds_read_b128 v[228:231], v222 offset:20480
	ds_read_b128 v[232:235], v222 offset:21504
	ds_read_b128 v[244:247], v222 offset:22528
	ds_read_b128 v[248:251], v222 offset:23552
	global_load_lds_dwordx4 v[198:199], off
	s_add_i32 m0, s6, 0x2000
	s_add_u32 s72, s56, 0x2000
	v_lshl_add_u64 v[198:199], s[56:57], 0, v[176:177]
	s_addc_u32 s73, s57, 0
	s_add_i32 s6, s7, s0
	global_load_lds_dwordx4 v[198:199], off
	v_lshl_add_u64 v[198:199], s[72:73], 0, v[172:173]
	s_mov_b32 m0, s6
	v_lshl_add_u64 v[200:201], s[58:59], 0, v[174:175]
	global_load_lds_dwordx4 v[198:199], off
	v_lshl_add_u64 v[198:199], s[72:73], 0, v[176:177]
	s_add_i32 m0, s6, 0x2000
	s_nop 0
	global_load_lds_dwordx4 v[198:199], off
	v_lshl_add_u64 v[198:199], s[58:59], 0, v[136:137]
	s_mov_b32 m0, s23
	s_nop 0
	global_load_lds_dwordx4 v[198:199], off
	s_mov_b32 m0, s24
	s_nop 0
	global_load_lds_dwordx4 v[200:201], off
	s_waitcnt vmcnt(8)
	s_waitcnt lgkmcnt(0)
	s_barrier
; #define PG8_STAGE(bufoff, gbase, voff) do { _Pragma("unroll") for (int _i = 0; _i < 2; ++_i) \
;         __builtin_amdgcn_global_load_lds((const unsigned*)((const char*)(gbase) + (voff)[_i]), (LAS unsigned*)(lds + (bufoff) + ldsw + _i * 8192), 16, 0, 0); } while (0)
; #define PG8_LDA(dst, b, h) do { _Pragma("unroll") for (int m = 0; m < 4; ++m) _Pragma("unroll") for (int k = 0; k < 2; ++k) dst[m][k] = *(const LAS bf16x8*)(lds + PG8_SA(b, h) + aoff + m * 2048 + k * 1024); } while (0)
; #define PG8_LDB(dst, b, h) do { _Pragma("unroll") for (int n = 0; n < 2; ++n) _Pragma("unroll") for (int k = 0; k < 2; ++k) dst[n][k] = *(const LAS bf16x8*)(lds + PG8_SB(b, h) + boff + n * 2048 + k * 1024); } while (0)
; #define PG8_MMA(ai, bj, At, Bt) do { __builtin_amdgcn_s_setprio(1); _Pragma("unroll") for (int m = 0; m < 4; ++m) _Pragma("unroll") for (int n = 0; n < 2; ++n) _Pragma("unroll") for (int k = 0; k < 2; ++k) \
;         acc[ai][bj][m][n] = __builtin_amdgcn_mfma_f32_16x16x32_bf16(Bt[n][k], At[m][k], acc[ai][bj][m][n], 0, 0, 0); __builtin_amdgcn_s_setprio(0); } while (0)
; #define PG8_WAIT_V(n) asm volatile("s_waitcnt vmcnt(" #n ")" ::: "memory")
; #define PG8_WAIT_L(n) asm volatile("s_waitcnt lgkmcnt(" #n ")" ::: "memory")
; #define PG8_BAR __builtin_amdgcn_s_barrier()
; #define PG8_SCHED __builtin_amdgcn_sched_barrier(0)
; template <class Epi, bool ALIGN_EPI>
; __device__ __forceinline__ void gemm_phase(LAS unsigned char* lds, const Gemm g, int G, int cid, const Epi& E) {
;     ...
;             PG8_WAIT_V(8); PG8_WAIT_L(0); PG8_BAR; PG8_MMA(1, 0, At, B0); PG8_MMA(1, 1, At, B1); PG8_BAR; PG8_SCHED;
;             PG8_LDB(B0, 1, 0); PG8_LDB(B1, 1, 1); PG8_SCHED; PG8_LDA(At, 1, 0); PG8_STAGE(PG8_SA(0, 1), a2 + hA, voffA);
;             PG8_WAIT_V(8); PG8_WAIT_L(0); PG8_BAR; PG8_MMA(0, 0, At, B0); PG8_MMA(0, 1, At, B1); PG8_BAR; PG8_SCHED;
	s_setprio 1
	v_mfma_f32_16x16x32_bf16 v[60:63], v[88:91], v[164:167], v[60:63]
	v_mfma_f32_16x16x32_bf16 v[56:59], v[104:107], v[164:167], v[56:59]
	v_mfma_f32_16x16x32_bf16 v[44:47], v[88:91], v[182:185], v[44:47]
	v_mfma_f32_16x16x32_bf16 v[40:43], v[104:107], v[182:185], v[40:43]
	v_mfma_f32_16x16x32_bf16 v[28:31], v[88:91], v[228:231], v[28:31]
	v_mfma_f32_16x16x32_bf16 v[24:27], v[104:107], v[228:231], v[24:27]
	v_mfma_f32_16x16x32_bf16 v[12:15], v[88:91], v[244:247], v[12:15]
	v_mfma_f32_16x16x32_bf16 v[8:11], v[104:107], v[244:247], v[8:11]
	v_mfma_f32_16x16x32_bf16 v[60:63], v[100:103], v[168:171], v[60:63]
	v_mfma_f32_16x16x32_bf16 v[56:59], v[108:111], v[168:171], v[56:59]
	v_mfma_f32_16x16x32_bf16 v[44:47], v[100:103], v[224:227], v[44:47]
	v_mfma_f32_16x16x32_bf16 v[40:43], v[108:111], v[224:227], v[40:43]
	v_mfma_f32_16x16x32_bf16 v[28:31], v[100:103], v[232:235], v[28:31]
	v_mfma_f32_16x16x32_bf16 v[24:27], v[108:111], v[232:235], v[24:27]
	v_mfma_f32_16x16x32_bf16 v[12:15], v[100:103], v[248:251], v[12:15]
	v_mfma_f32_16x16x32_bf16 v[8:11], v[108:111], v[248:251], v[8:11]
	s_setprio 0
	s_setprio 1
	v_mfma_f32_16x16x32_bf16 v[52:55], v[112:115], v[164:167], v[52:55]
	v_mfma_f32_16x16x32_bf16 v[48:51], v[124:127], v[164:167], v[48:51]
	v_mfma_f32_16x16x32_bf16 v[36:39], v[112:115], v[182:185], v[36:39]
	v_mfma_f32_16x16x32_bf16 v[32:35], v[124:127], v[182:185], v[32:35]
	v_mfma_f32_16x16x32_bf16 v[20:23], v[112:115], v[228:231], v[20:23]
	v_mfma_f32_16x16x32_bf16 v[16:19], v[124:127], v[228:231], v[16:19]
	v_mfma_f32_16x16x32_bf16 v[4:7], v[112:115], v[244:247], v[4:7]
	v_mfma_f32_16x16x32_bf16 v[0:3], v[124:127], v[244:247], v[0:3]
	v_mfma_f32_16x16x32_bf16 v[52:55], v[120:123], v[168:171], v[52:55]
	v_mfma_f32_16x16x32_bf16 v[48:51], v[132:135], v[168:171], v[48:51]
	v_mfma_f32_16x16x32_bf16 v[36:39], v[120:123], v[224:227], v[36:39]
	v_mfma_f32_16x16x32_bf16 v[32:35], v[132:135], v[224:227], v[32:35]
	v_mfma_f32_16x16x32_bf16 v[20:23], v[120:123], v[232:235], v[20:23]
	v_mfma_f32_16x16x32_bf16 v[16:19], v[132:135], v[232:235], v[16:19]
	v_mfma_f32_16x16x32_bf16 v[4:7], v[120:123], v[248:251], v[4:7]
	v_mfma_f32_16x16x32_bf16 v[0:3], v[132:135], v[248:251], v[0:3]
	s_setprio 0
	s_barrier
	s_add_i32 s6, 0, 0x18000
	s_add_i32 s7, 0, 0x1c000
	v_add_u32_e32 v108, s6, v190
	v_add_u32_e32 v132, s7, v190
	ds_read_b128 v[88:91], v108
	ds_read_b128 v[100:103], v108 offset:1024
	ds_read_b128 v[104:107], v108 offset:2048
	ds_read_b128 v[108:111], v108 offset:3072
	ds_read_b128 v[112:115], v132
	ds_read_b128 v[120:123], v132 offset:1024
	ds_read_b128 v[124:127], v132 offset:2048
	ds_read_b128 v[132:135], v132 offset:3072
	s_add_u32 s58, s58, 0x84000
	s_addc_u32 s59, s59, 0
	s_mov_b32 m0, s25
	v_lshl_add_u64 v[242:243], s[58:59], 0, v[136:137]
	ds_read_b128 v[164:167], v222 offset:32768
	ds_read_b128 v[168:171], v222 offset:33792
	ds_read_b128 v[182:185], v222 offset:34816
	ds_read_b128 v[224:227], v222 offset:35840
	ds_read_b128 v[228:231], v222 offset:36864
	ds_read_b128 v[232:235], v222 offset:37888
	ds_read_b128 v[244:247], v222 offset:38912
	ds_read_b128 v[248:251], v222 offset:39936
	global_load_lds_dwordx4 v[242:243], off
	v_lshl_add_u64 v[242:243], s[58:59], 0, v[174:175]
	s_mov_b32 m0, s76
	s_nop 0
	global_load_lds_dwordx4 v[242:243], off
	s_waitcnt vmcnt(8)
	s_waitcnt lgkmcnt(0)
	s_barrier
	s_setprio 1
	v_mfma_f32_16x16x32_bf16 v[160:163], v[88:91], v[164:167], v[160:163]
	v_mfma_f32_16x16x32_bf16 v[156:159], v[104:107], v[164:167], v[156:159]
	v_mfma_f32_16x16x32_bf16 v[144:147], v[88:91], v[182:185], v[144:147]
	v_mfma_f32_16x16x32_bf16 v[140:143], v[104:107], v[182:185], v[140:143]
	v_mfma_f32_16x16x32_bf16 v[96:99], v[88:91], v[228:231], v[96:99]
	v_mfma_f32_16x16x32_bf16 v[92:95], v[104:107], v[228:231], v[92:95]
	v_mfma_f32_16x16x32_bf16 v[76:79], v[88:91], v[244:247], v[76:79]
	v_mfma_f32_16x16x32_bf16 v[72:75], v[104:107], v[244:247], v[72:75]
	v_mfma_f32_16x16x32_bf16 v[160:163], v[100:103], v[168:171], v[160:163]
	v_mfma_f32_16x16x32_bf16 v[156:159], v[108:111], v[168:171], v[156:159]
	v_mfma_f32_16x16x32_bf16 v[144:147], v[100:103], v[224:227], v[144:147]
	v_mfma_f32_16x16x32_bf16 v[140:143], v[108:111], v[224:227], v[140:143]
	v_mfma_f32_16x16x32_bf16 v[96:99], v[100:103], v[232:235], v[96:99]
	v_mfma_f32_16x16x32_bf16 v[92:95], v[108:111], v[232:235], v[92:95]
	v_mfma_f32_16x16x32_bf16 v[76:79], v[100:103], v[248:251], v[76:79]
	v_mfma_f32_16x16x32_bf16 v[72:75], v[108:111], v[248:251], v[72:75]
	s_setprio 0
	s_setprio 1
	v_mfma_f32_16x16x32_bf16 v[152:155], v[112:115], v[164:167], v[152:155]
	v_mfma_f32_16x16x32_bf16 v[148:151], v[124:127], v[164:167], v[148:151]
	v_mfma_f32_16x16x32_bf16 v[128:131], v[112:115], v[182:185], v[128:131]
	v_mfma_f32_16x16x32_bf16 v[116:119], v[124:127], v[182:185], v[116:119]
	v_mfma_f32_16x16x32_bf16 v[84:87], v[112:115], v[228:231], v[84:87]
	v_mfma_f32_16x16x32_bf16 v[80:83], v[124:127], v[228:231], v[80:83]
	v_mfma_f32_16x16x32_bf16 v[68:71], v[112:115], v[244:247], v[68:71]
	v_mfma_f32_16x16x32_bf16 v[64:67], v[124:127], v[244:247], v[64:67]
	v_mfma_f32_16x16x32_bf16 v[152:155], v[120:123], v[168:171], v[152:155]
	v_mfma_f32_16x16x32_bf16 v[148:151], v[132:135], v[168:171], v[148:151]
	v_mfma_f32_16x16x32_bf16 v[128:131], v[120:123], v[224:227], v[128:131]
	v_mfma_f32_16x16x32_bf16 v[116:119], v[132:135], v[224:227], v[116:119]
	v_mfma_f32_16x16x32_bf16 v[84:87], v[120:123], v[232:235], v[84:87]
	v_mfma_f32_16x16x32_bf16 v[80:83], v[132:135], v[232:235], v[80:83]
	v_mfma_f32_16x16x32_bf16 v[68:71], v[120:123], v[248:251], v[68:71]
	v_mfma_f32_16x16x32_bf16 v[64:67], v[132:135], v[248:251], v[64:67]
	s_setprio 0
	s_barrier
; #define PG8_STAGE(bufoff, gbase, voff) do { _Pragma("unroll") for (int _i = 0; _i < 2; ++_i) \
;         __builtin_amdgcn_global_load_lds((const unsigned*)((const char*)(gbase) + (voff)[_i]), (LAS unsigned*)(lds + (bufoff) + ldsw + _i * 8192), 16, 0, 0); } while (0)
; #define PG8_LDA(dst, b, h) do { _Pragma("unroll") for (int m = 0; m < 4; ++m) _Pragma("unroll") for (int k = 0; k < 2; ++k) dst[m][k] = *(const LAS bf16x8*)(lds + PG8_SA(b, h) + aoff + m * 2048 + k * 1024); } while (0)
; #define PG8_MMA(ai, bj, At, Bt) do { __builtin_amdgcn_s_setprio(1); _Pragma("unroll") for (int m = 0; m < 4; ++m) _Pragma("unroll") for (int n = 0; n < 2; ++n) _Pragma("unroll") for (int k = 0; k < 2; ++k) \
;         acc[ai][bj][m][n] = __builtin_amdgcn_mfma_f32_16x16x32_bf16(Bt[n][k], At[m][k], acc[ai][bj][m][n], 0, 0, 0); __builtin_amdgcn_s_setprio(0); } while (0)
; #define PG8_WAIT_V(n) asm volatile("s_waitcnt vmcnt(" #n ")" ::: "memory")
; #define PG8_WAIT_L(n) asm volatile("s_waitcnt lgkmcnt(" #n ")" ::: "memory")
; #define PG8_BAR __builtin_amdgcn_s_barrier()
; #define PG8_SCHED __builtin_amdgcn_sched_barrier(0)
; template <class Epi, bool ALIGN_EPI>
; __device__ __forceinline__ void gemm_phase(LAS unsigned char* lds, const Gemm g, int G, int cid, const Epi& E) {
;     ...
;             PG8_LDA(At, 1, 1); PG8_STAGE(PG8_SB(1, 0), b3, voffB); PG8_STAGE(PG8_SB(1, 1), b3 + hB, voffB); PG8_STAGE(PG8_SA(1, 0), a3, voffA);
;             PG8_WAIT_V(8); PG8_WAIT_L(0); PG8_BAR; PG8_MMA(1, 0, At, B0); PG8_MMA(1, 1, At, B1); PG8_BAR; PG8_SCHED;
	s_add_u32 s58, s56, 0xc0000
	s_addc_u32 s59, s57, 0
	s_add_i32 s6, s6, s0
	v_lshl_add_u64 v[242:243], s[58:59], 0, v[172:173]
	s_mov_b32 m0, s6
	ds_read_b128 v[164:167], v222 offset:49152
	ds_read_b128 v[168:171], v222 offset:50176
	ds_read_b128 v[182:185], v222 offset:51200
	ds_read_b128 v[224:227], v222 offset:52224
	ds_read_b128 v[228:231], v222 offset:53248
	ds_read_b128 v[232:235], v222 offset:54272
	ds_read_b128 v[244:247], v222 offset:55296
	ds_read_b128 v[248:251], v222 offset:56320
	global_load_lds_dwordx4 v[242:243], off
	s_add_i32 m0, s6, 0x2000
	s_add_u32 s56, s56, 0xc2000
	v_lshl_add_u64 v[242:243], s[58:59], 0, v[176:177]
	s_addc_u32 s57, s57, 0
	s_add_i32 s6, s7, s0
	global_load_lds_dwordx4 v[242:243], off
	v_lshl_add_u64 v[242:243], s[56:57], 0, v[172:173]
	s_mov_b32 m0, s6
	v_lshl_add_u64 v[198:199], v[198:199], 0, s[36:37]
	global_load_lds_dwordx4 v[242:243], off
	v_lshl_add_u64 v[242:243], s[56:57], 0, v[176:177]
	s_add_i32 m0, s6, 0x2000
	s_nop 0
	global_load_lds_dwordx4 v[242:243], off
	s_mov_b32 m0, s78
	s_nop 0
	global_load_lds_dwordx4 v[198:199], off
	v_lshl_add_u64 v[198:199], v[200:201], 0, s[36:37]
	s_mov_b32 m0, s79
	s_nop 0
	global_load_lds_dwordx4 v[198:199], off
	s_waitcnt vmcnt(8)
	s_waitcnt lgkmcnt(0)
	s_barrier
	s_setprio 1
	v_mfma_f32_16x16x32_bf16 v[60:63], v[88:91], v[164:167], v[60:63]
	v_mfma_f32_16x16x32_bf16 v[56:59], v[104:107], v[164:167], v[56:59]
	v_mfma_f32_16x16x32_bf16 v[44:47], v[88:91], v[182:185], v[44:47]
	v_mfma_f32_16x16x32_bf16 v[40:43], v[104:107], v[182:185], v[40:43]
	v_mfma_f32_16x16x32_bf16 v[28:31], v[88:91], v[228:231], v[28:31]
	v_mfma_f32_16x16x32_bf16 v[24:27], v[104:107], v[228:231], v[24:27]
	v_mfma_f32_16x16x32_bf16 v[12:15], v[88:91], v[244:247], v[12:15]
	v_mfma_f32_16x16x32_bf16 v[8:11], v[104:107], v[244:247], v[8:11]
	v_mfma_f32_16x16x32_bf16 v[60:63], v[100:103], v[168:171], v[60:63]
	v_mfma_f32_16x16x32_bf16 v[56:59], v[108:111], v[168:171], v[56:59]
	v_mfma_f32_16x16x32_bf16 v[44:47], v[100:103], v[224:227], v[44:47]
	v_mfma_f32_16x16x32_bf16 v[40:43], v[108:111], v[224:227], v[40:43]
	v_mfma_f32_16x16x32_bf16 v[28:31], v[100:103], v[232:235], v[28:31]
	v_mfma_f32_16x16x32_bf16 v[24:27], v[108:111], v[232:235], v[24:27]
	v_mfma_f32_16x16x32_bf16 v[12:15], v[100:103], v[248:251], v[12:15]
	v_mfma_f32_16x16x32_bf16 v[8:11], v[108:111], v[248:251], v[8:11]
	s_setprio 0
	s_setprio 1
	v_mfma_f32_16x16x32_bf16 v[52:55], v[112:115], v[164:167], v[52:55]
	v_mfma_f32_16x16x32_bf16 v[48:51], v[124:127], v[164:167], v[48:51]
	v_mfma_f32_16x16x32_bf16 v[36:39], v[112:115], v[182:185], v[36:39]
	v_mfma_f32_16x16x32_bf16 v[32:35], v[124:127], v[182:185], v[32:35]
	v_mfma_f32_16x16x32_bf16 v[20:23], v[112:115], v[228:231], v[20:23]
	v_mfma_f32_16x16x32_bf16 v[16:19], v[124:127], v[228:231], v[16:19]
	v_mfma_f32_16x16x32_bf16 v[4:7], v[112:115], v[244:247], v[4:7]
	v_mfma_f32_16x16x32_bf16 v[0:3], v[124:127], v[244:247], v[0:3]
	v_mfma_f32_16x16x32_bf16 v[52:55], v[120:123], v[168:171], v[52:55]
	v_mfma_f32_16x16x32_bf16 v[48:51], v[132:135], v[168:171], v[48:51]
	v_mfma_f32_16x16x32_bf16 v[36:39], v[120:123], v[224:227], v[36:39]
	v_mfma_f32_16x16x32_bf16 v[32:35], v[132:135], v[224:227], v[32:35]
	v_mfma_f32_16x16x32_bf16 v[20:23], v[120:123], v[232:235], v[20:23]
	v_mfma_f32_16x16x32_bf16 v[16:19], v[132:135], v[232:235], v[16:19]
	v_mfma_f32_16x16x32_bf16 v[4:7], v[120:123], v[248:251], v[4:7]
	v_mfma_f32_16x16x32_bf16 v[0:3], v[132:135], v[248:251], v[0:3]
	s_setprio 0
	s_barrier
	s_add_i32 s30, s30, 2
	s_add_u32 s54, s54, 0x180000
	s_addc_u32 s55, s55, 0
	s_cmp_gt_u32 s30, 29
	s_mov_b64 s[72:73], s[74:75]
	s_cbranch_scc1 .LBB0_269

; #define PG8_STAGE(bufoff, gbase, voff) do { _Pragma("unroll") for (int _i = 0; _i < 2; ++_i) \
;         __builtin_amdgcn_global_load_lds((const unsigned*)((const char*)(gbase) + (voff)[_i]), (LAS unsigned*)(lds + (bufoff) + ldsw + _i * 8192), 16, 0, 0); } while (0)
; #define PG8_LDA(dst, b, h) do { _Pragma("unroll") for (int m = 0; m < 4; ++m) _Pragma("unroll") for (int k = 0; k < 2; ++k) dst[m][k] = *(const LAS bf16x8*)(lds + PG8_SA(b, h) + aoff + m * 2048 + k * 1024); } while (0)
; #define PG8_LDB(dst, b, h) do { _Pragma("unroll") for (int n = 0; n < 2; ++n) _Pragma("unroll") for (int k = 0; k < 2; ++k) dst[n][k] = *(const LAS bf16x8*)(lds + PG8_SB(b, h) + boff + n * 2048 + k * 1024); } while (0)
; #define PG8_MMA(ai, bj, At, Bt) do { __builtin_amdgcn_s_setprio(1); _Pragma("unroll") for (int m = 0; m < 4; ++m) _Pragma("unroll") for (int n = 0; n < 2; ++n) _Pragma("unroll") for (int k = 0; k < 2; ++k) \
;         acc[ai][bj][m][n] = __builtin_amdgcn_mfma_f32_16x16x32_bf16(Bt[n][k], At[m][k], acc[ai][bj][m][n], 0, 0, 0); __builtin_amdgcn_s_setprio(0); } while (0)
; #define PG8_WAIT_V(n) asm volatile("s_waitcnt vmcnt(" #n ")" ::: "memory")
; #define PG8_WAIT_L(n) asm volatile("s_waitcnt lgkmcnt(" #n ")" ::: "memory")
; #define PG8_BAR __builtin_amdgcn_s_barrier()
; #define PG8_SCHED __builtin_amdgcn_sched_barrier(0)
; template <class Epi, bool ALIGN_EPI>
; __device__ __forceinline__ void gemm_phase(LAS unsigned char* lds, const Gemm g, int G, int cid, const Epi& E) {
;     ...
;             PG8_LDB(B0, 0, 0); PG8_LDB(B1, 0, 1); PG8_SCHED; PG8_LDA(At, 0, 0); PG8_STAGE(PG8_SA(1, 1), a1 + hA, voffA);
;             PG8_WAIT_V(8); PG8_WAIT_L(0); PG8_BAR; PG8_MMA(0, 0, At, B0); PG8_MMA(0, 1, At, B1); PG8_BAR; PG8_SCHED;
;             PG8_LDA(At, 0, 1); PG8_STAGE(PG8_SB(0, 0), b2, voffB); PG8_STAGE(PG8_SB(0, 1), b2 + hB, voffB); PG8_STAGE(PG8_SA(0, 0), a2, voffA);
;             PG8_WAIT_V(8); PG8_WAIT_L(0); PG8_BAR; PG8_MMA(1, 0, At, B0); PG8_MMA(1, 1, At, B1); PG8_BAR; PG8_SCHED;
.LBB0_727:
	s_add_u32 s42, s46, 0x100
	s_addc_u32 s43, s47, 0
	s_add_i32 s6, 0, 0x10000
	s_cmp_eq_u32 s77, 28
	s_cselect_b32 s51, s29, s43
	s_cselect_b32 s50, s28, s42
	s_cselect_b32 s49, s30, s76
	s_cselect_b32 s48, s74, s75
	s_add_i32 s7, 0, 0x14000
	v_add_u32_e32 v132, s6, v220
	v_add_u32_e32 v160, s7, v220
	ds_read_b128 v[112:115], v132
	ds_read_b128 v[116:119], v132 offset:1024
	ds_read_b128 v[128:131], v132 offset:2048
	ds_read_b128 v[132:135], v132 offset:3072
	ds_read_b128 v[140:143], v160
	ds_read_b128 v[144:147], v160 offset:1024
	ds_read_b128 v[156:159], v160 offset:2048
	ds_read_b128 v[160:163], v160 offset:3072
	v_lshl_add_u64 v[198:199], s[46:47], 0, v[184:185]
	s_add_i32 m0, s52, 0xc000
	ds_read_b128 v[164:167], v222
	ds_read_b128 v[168:171], v222 offset:1024
	ds_read_b128 v[172:175], v222 offset:2048
	ds_read_b128 v[176:179], v222 offset:3072
	ds_read_b128 v[188:191], v222 offset:4096
	ds_read_b128 v[206:209], v222 offset:5120
	ds_read_b128 v[210:213], v222 offset:6144
	ds_read_b128 v[214:217], v222 offset:7168
	global_load_lds_dwordx4 v[198:199], off
	v_lshl_add_u64 v[198:199], s[46:47], 0, v[186:187]
	s_add_i32 m0, s52, 0xe000
	s_nop 0
	global_load_lds_dwordx4 v[198:199], off
	s_add_i32 vcc_lo, s77, 2
	s_lshl_b32 vcc_lo, vcc_lo, 16
	s_lshl_b32 vcc_hi, s13, 21
	s_add_i32 vcc_lo, vcc_lo, vcc_hi
	s_lshl_b32 vcc_hi, s25, 4
	s_add_i32 vcc_lo, vcc_lo, vcc_hi
	s_lshl_b32 vcc_hi, s12, 10
	s_add_i32 vcc_lo, vcc_lo, vcc_hi
	s_add_u32 vcc_lo, s22, vcc_lo
	s_addc_u32 vcc_hi, s23, 0
	s_mov_b32 m0, 0x22c00
	s_nop 0
	global_load_lds_dwordx4 v224, vcc
	s_waitcnt vmcnt(9)
	s_waitcnt lgkmcnt(0)
	s_barrier
	s_setprio 1
	v_mfma_f32_16x16x32_bf16 v[152:155], v[112:115], v[164:167], v[152:155]
	v_mfma_f32_16x16x32_bf16 v[148:151], v[128:131], v[164:167], v[148:151]
	v_mfma_f32_16x16x32_bf16 v[108:111], v[112:115], v[172:175], v[108:111]
	v_mfma_f32_16x16x32_bf16 v[104:107], v[128:131], v[172:175], v[104:107]
	v_mfma_f32_16x16x32_bf16 v[92:95], v[112:115], v[188:191], v[92:95]
	v_mfma_f32_16x16x32_bf16 v[88:91], v[128:131], v[188:191], v[88:91]
	v_mfma_f32_16x16x32_bf16 v[76:79], v[112:115], v[210:213], v[76:79]
	v_mfma_f32_16x16x32_bf16 v[72:75], v[128:131], v[210:213], v[72:75]
	v_mfma_f32_16x16x32_bf16 v[152:155], v[116:119], v[168:171], v[152:155]
	v_mfma_f32_16x16x32_bf16 v[148:151], v[132:135], v[168:171], v[148:151]
	v_mfma_f32_16x16x32_bf16 v[108:111], v[116:119], v[176:179], v[108:111]
	v_mfma_f32_16x16x32_bf16 v[104:107], v[132:135], v[176:179], v[104:107]
	v_mfma_f32_16x16x32_bf16 v[92:95], v[116:119], v[206:209], v[92:95]
	v_mfma_f32_16x16x32_bf16 v[88:91], v[132:135], v[206:209], v[88:91]
	v_mfma_f32_16x16x32_bf16 v[76:79], v[116:119], v[214:217], v[76:79]
	v_mfma_f32_16x16x32_bf16 v[72:75], v[132:135], v[214:217], v[72:75]
	s_setprio 0
	s_setprio 1
	v_mfma_f32_16x16x32_bf16 v[124:127], v[140:143], v[164:167], v[124:127]
	v_mfma_f32_16x16x32_bf16 v[120:123], v[156:159], v[164:167], v[120:123]
	v_mfma_f32_16x16x32_bf16 v[100:103], v[140:143], v[172:175], v[100:103]
	v_mfma_f32_16x16x32_bf16 v[96:99], v[156:159], v[172:175], v[96:99]
	v_mfma_f32_16x16x32_bf16 v[84:87], v[140:143], v[188:191], v[84:87]
	v_mfma_f32_16x16x32_bf16 v[80:83], v[156:159], v[188:191], v[80:83]
	v_mfma_f32_16x16x32_bf16 v[68:71], v[140:143], v[210:213], v[68:71]
	v_mfma_f32_16x16x32_bf16 v[64:67], v[156:159], v[210:213], v[64:67]
	v_mfma_f32_16x16x32_bf16 v[124:127], v[144:147], v[168:171], v[124:127]
	v_mfma_f32_16x16x32_bf16 v[120:123], v[160:163], v[168:171], v[120:123]
	v_mfma_f32_16x16x32_bf16 v[100:103], v[144:147], v[176:179], v[100:103]
	v_mfma_f32_16x16x32_bf16 v[96:99], v[160:163], v[176:179], v[96:99]
	v_mfma_f32_16x16x32_bf16 v[84:87], v[144:147], v[206:209], v[84:87]
	v_mfma_f32_16x16x32_bf16 v[80:83], v[160:163], v[206:209], v[80:83]
	v_mfma_f32_16x16x32_bf16 v[68:71], v[144:147], v[214:217], v[68:71]
	v_mfma_f32_16x16x32_bf16 v[64:67], v[160:163], v[214:217], v[64:67]
	s_setprio 0
	s_barrier
	s_add_i32 s6, s6, s25
	v_lshl_add_u64 v[198:199], s[48:49], 0, v[138:139]
	s_mov_b32 m0, s6
	ds_read_b128 v[164:167], v222 offset:16384
	ds_read_b128 v[168:171], v222 offset:17408
	ds_read_b128 v[172:175], v222 offset:18432
	ds_read_b128 v[176:179], v222 offset:19456
	ds_read_b128 v[188:191], v222 offset:20480
	ds_read_b128 v[206:209], v222 offset:21504
	ds_read_b128 v[210:213], v222 offset:22528
	ds_read_b128 v[214:217], v222 offset:23552
	global_load_lds_dwordx4 v[198:199], off
	s_add_i32 m0, s6, 0x2000
	s_add_u32 s46, s48, 0x2000
	v_lshl_add_u64 v[198:199], s[48:49], 0, v[136:137]
	s_addc_u32 s47, s49, 0
	s_add_i32 s6, s7, s25
	global_load_lds_dwordx4 v[198:199], off
	v_lshl_add_u64 v[198:199], s[46:47], 0, v[138:139]
	s_mov_b32 m0, s6
	v_lshl_add_u64 v[200:201], s[50:51], 0, v[180:181]
	global_load_lds_dwordx4 v[198:199], off
	v_lshl_add_u64 v[198:199], s[46:47], 0, v[136:137]
	s_add_i32 m0, s6, 0x2000
	s_nop 0
	global_load_lds_dwordx4 v[198:199], off
	v_lshl_add_u64 v[198:199], s[50:51], 0, v[182:183]
	s_mov_b32 m0, s52
	s_nop 0
	global_load_lds_dwordx4 v[198:199], off
	s_mov_b32 m0, s53
	s_nop 0
	global_load_lds_dwordx4 v[200:201], off
	s_waitcnt vmcnt(9)
	s_waitcnt lgkmcnt(0)
	s_barrier
; #define PG8_STAGE(bufoff, gbase, voff) do { _Pragma("unroll") for (int _i = 0; _i < 2; ++_i) \
;         __builtin_amdgcn_global_load_lds((const unsigned*)((const char*)(gbase) + (voff)[_i]), (LAS unsigned*)(lds + (bufoff) + ldsw + _i * 8192), 16, 0, 0); } while (0)
; #define PG8_LDA(dst, b, h) do { _Pragma("unroll") for (int m = 0; m < 4; ++m) _Pragma("unroll") for (int k = 0; k < 2; ++k) dst[m][k] = *(const LAS bf16x8*)(lds + PG8_SA(b, h) + aoff + m * 2048 + k * 1024); } while (0)
; #define PG8_LDB(dst, b, h) do { _Pragma("unroll") for (int n = 0; n < 2; ++n) _Pragma("unroll") for (int k = 0; k < 2; ++k) dst[n][k] = *(const LAS bf16x8*)(lds + PG8_SB(b, h) + boff + n * 2048 + k * 1024); } while (0)
; #define PG8_MMA(ai, bj, At, Bt) do { __builtin_amdgcn_s_setprio(1); _Pragma("unroll") for (int m = 0; m < 4; ++m) _Pragma("unroll") for (int n = 0; n < 2; ++n) _Pragma("unroll") for (int k = 0; k < 2; ++k) \
;         acc[ai][bj][m][n] = __builtin_amdgcn_mfma_f32_16x16x32_bf16(Bt[n][k], At[m][k], acc[ai][bj][m][n], 0, 0, 0); __builtin_amdgcn_s_setprio(0); } while (0)
; #define PG8_WAIT_V(n) asm volatile("s_waitcnt vmcnt(" #n ")" ::: "memory")
; #define PG8_WAIT_L(n) asm volatile("s_waitcnt lgkmcnt(" #n ")" ::: "memory")
; #define PG8_BAR __builtin_amdgcn_s_barrier()
; #define PG8_SCHED __builtin_amdgcn_sched_barrier(0)
; template <class Epi, bool ALIGN_EPI>
; __device__ __forceinline__ void gemm_phase(LAS unsigned char* lds, const Gemm g, int G, int cid, const Epi& E) {
;     ...
;             PG8_WAIT_V(8); PG8_WAIT_L(0); PG8_BAR; PG8_MMA(1, 0, At, B0); PG8_MMA(1, 1, At, B1); PG8_BAR; PG8_SCHED;
;             PG8_LDB(B0, 1, 0); PG8_LDB(B1, 1, 1); PG8_SCHED; PG8_LDA(At, 1, 0); PG8_STAGE(PG8_SA(0, 1), a2 + hA, voffA);
;             PG8_WAIT_V(8); PG8_WAIT_L(0); PG8_BAR; PG8_MMA(0, 0, At, B0); PG8_MMA(0, 1, At, B1); PG8_BAR; PG8_SCHED;
	s_setprio 1
	v_mfma_f32_16x16x32_bf16 v[60:63], v[112:115], v[164:167], v[60:63]
	v_mfma_f32_16x16x32_bf16 v[56:59], v[128:131], v[164:167], v[56:59]
	v_mfma_f32_16x16x32_bf16 v[44:47], v[112:115], v[172:175], v[44:47]
	v_mfma_f32_16x16x32_bf16 v[40:43], v[128:131], v[172:175], v[40:43]
	v_mfma_f32_16x16x32_bf16 v[28:31], v[112:115], v[188:191], v[28:31]
	v_mfma_f32_16x16x32_bf16 v[24:27], v[128:131], v[188:191], v[24:27]
	v_mfma_f32_16x16x32_bf16 v[12:15], v[112:115], v[210:213], v[12:15]
	v_mfma_f32_16x16x32_bf16 v[8:11], v[128:131], v[210:213], v[8:11]
	v_mfma_f32_16x16x32_bf16 v[60:63], v[116:119], v[168:171], v[60:63]
	v_mfma_f32_16x16x32_bf16 v[56:59], v[132:135], v[168:171], v[56:59]
	v_mfma_f32_16x16x32_bf16 v[44:47], v[116:119], v[176:179], v[44:47]
	v_mfma_f32_16x16x32_bf16 v[40:43], v[132:135], v[176:179], v[40:43]
	v_mfma_f32_16x16x32_bf16 v[28:31], v[116:119], v[206:209], v[28:31]
	v_mfma_f32_16x16x32_bf16 v[24:27], v[132:135], v[206:209], v[24:27]
	v_mfma_f32_16x16x32_bf16 v[12:15], v[116:119], v[214:217], v[12:15]
	v_mfma_f32_16x16x32_bf16 v[8:11], v[132:135], v[214:217], v[8:11]
	s_setprio 0
	s_setprio 1
	v_mfma_f32_16x16x32_bf16 v[52:55], v[140:143], v[164:167], v[52:55]
	v_mfma_f32_16x16x32_bf16 v[48:51], v[156:159], v[164:167], v[48:51]
	v_mfma_f32_16x16x32_bf16 v[36:39], v[140:143], v[172:175], v[36:39]
	v_mfma_f32_16x16x32_bf16 v[32:35], v[156:159], v[172:175], v[32:35]
	v_mfma_f32_16x16x32_bf16 v[20:23], v[140:143], v[188:191], v[20:23]
	v_mfma_f32_16x16x32_bf16 v[16:19], v[156:159], v[188:191], v[16:19]
	v_mfma_f32_16x16x32_bf16 v[4:7], v[140:143], v[210:213], v[4:7]
	v_mfma_f32_16x16x32_bf16 v[0:3], v[156:159], v[210:213], v[0:3]
	v_mfma_f32_16x16x32_bf16 v[52:55], v[144:147], v[168:171], v[52:55]
	v_mfma_f32_16x16x32_bf16 v[48:51], v[160:163], v[168:171], v[48:51]
	v_mfma_f32_16x16x32_bf16 v[36:39], v[144:147], v[176:179], v[36:39]
	v_mfma_f32_16x16x32_bf16 v[32:35], v[160:163], v[176:179], v[32:35]
	v_mfma_f32_16x16x32_bf16 v[20:23], v[144:147], v[206:209], v[20:23]
	v_mfma_f32_16x16x32_bf16 v[16:19], v[160:163], v[206:209], v[16:19]
	v_mfma_f32_16x16x32_bf16 v[4:7], v[144:147], v[214:217], v[4:7]
	v_mfma_f32_16x16x32_bf16 v[0:3], v[160:163], v[214:217], v[0:3]
	s_setprio 0
	s_barrier
	s_add_i32 s6, 0, 0x18000
	s_add_i32 s7, 0, 0x1c000
	v_add_u32_e32 v132, s6, v220
	v_add_u32_e32 v160, s7, v220
	ds_read_b128 v[112:115], v132
	ds_read_b128 v[116:119], v132 offset:1024
	ds_read_b128 v[128:131], v132 offset:2048
	ds_read_b128 v[132:135], v132 offset:3072
	ds_read_b128 v[140:143], v160
	ds_read_b128 v[144:147], v160 offset:1024
	ds_read_b128 v[156:159], v160 offset:2048
	ds_read_b128 v[160:163], v160 offset:3072
	s_add_u32 s46, s50, 0x84000
	s_addc_u32 s47, s51, 0
	s_mov_b32 m0, s54
	v_lshl_add_u64 v[218:219], s[46:47], 0, v[182:183]
	ds_read_b128 v[164:167], v222 offset:32768
	ds_read_b128 v[168:171], v222 offset:33792
	ds_read_b128 v[172:175], v222 offset:34816
	ds_read_b128 v[176:179], v222 offset:35840
	ds_read_b128 v[188:191], v222 offset:36864
	ds_read_b128 v[206:209], v222 offset:37888
	ds_read_b128 v[210:213], v222 offset:38912
	ds_read_b128 v[214:217], v222 offset:39936
	global_load_lds_dwordx4 v[218:219], off
	v_lshl_add_u64 v[218:219], s[46:47], 0, v[180:181]
	s_mov_b32 m0, s55
	s_nop 0
	global_load_lds_dwordx4 v[218:219], off
	s_add_u32 vcc_lo, vcc_lo, 0x2000
	s_addc_u32 vcc_hi, vcc_hi, 0
	s_mov_b32 m0, 0x22c00
	s_nop 0
	global_load_lds_dwordx4 v224, vcc
	s_waitcnt vmcnt(9)
	s_waitcnt lgkmcnt(0)
	s_barrier
	s_setprio 1
	v_mfma_f32_16x16x32_bf16 v[152:155], v[112:115], v[164:167], v[152:155]
	v_mfma_f32_16x16x32_bf16 v[148:151], v[128:131], v[164:167], v[148:151]
	v_mfma_f32_16x16x32_bf16 v[108:111], v[112:115], v[172:175], v[108:111]
	v_mfma_f32_16x16x32_bf16 v[104:107], v[128:131], v[172:175], v[104:107]
	v_mfma_f32_16x16x32_bf16 v[92:95], v[112:115], v[188:191], v[92:95]
	v_mfma_f32_16x16x32_bf16 v[88:91], v[128:131], v[188:191], v[88:91]
	v_mfma_f32_16x16x32_bf16 v[76:79], v[112:115], v[210:213], v[76:79]
	v_mfma_f32_16x16x32_bf16 v[72:75], v[128:131], v[210:213], v[72:75]
	v_mfma_f32_16x16x32_bf16 v[152:155], v[116:119], v[168:171], v[152:155]
	v_mfma_f32_16x16x32_bf16 v[148:151], v[132:135], v[168:171], v[148:151]
	v_mfma_f32_16x16x32_bf16 v[108:111], v[116:119], v[176:179], v[108:111]
	v_mfma_f32_16x16x32_bf16 v[104:107], v[132:135], v[176:179], v[104:107]
	v_mfma_f32_16x16x32_bf16 v[92:95], v[116:119], v[206:209], v[92:95]
	v_mfma_f32_16x16x32_bf16 v[88:91], v[132:135], v[206:209], v[88:91]
	v_mfma_f32_16x16x32_bf16 v[76:79], v[116:119], v[214:217], v[76:79]
	v_mfma_f32_16x16x32_bf16 v[72:75], v[132:135], v[214:217], v[72:75]
	s_setprio 0
	s_setprio 1
	v_mfma_f32_16x16x32_bf16 v[124:127], v[140:143], v[164:167], v[124:127]
	v_mfma_f32_16x16x32_bf16 v[120:123], v[156:159], v[164:167], v[120:123]
	v_mfma_f32_16x16x32_bf16 v[100:103], v[140:143], v[172:175], v[100:103]
	v_mfma_f32_16x16x32_bf16 v[96:99], v[156:159], v[172:175], v[96:99]
	v_mfma_f32_16x16x32_bf16 v[84:87], v[140:143], v[188:191], v[84:87]
	v_mfma_f32_16x16x32_bf16 v[80:83], v[156:159], v[188:191], v[80:83]
	v_mfma_f32_16x16x32_bf16 v[68:71], v[140:143], v[210:213], v[68:71]
	v_mfma_f32_16x16x32_bf16 v[64:67], v[156:159], v[210:213], v[64:67]
	v_mfma_f32_16x16x32_bf16 v[124:127], v[144:147], v[168:171], v[124:127]
	v_mfma_f32_16x16x32_bf16 v[120:123], v[160:163], v[168:171], v[120:123]
	v_mfma_f32_16x16x32_bf16 v[100:103], v[144:147], v[176:179], v[100:103]
	v_mfma_f32_16x16x32_bf16 v[96:99], v[160:163], v[176:179], v[96:99]
	v_mfma_f32_16x16x32_bf16 v[84:87], v[144:147], v[206:209], v[84:87]
	v_mfma_f32_16x16x32_bf16 v[80:83], v[160:163], v[206:209], v[80:83]
	v_mfma_f32_16x16x32_bf16 v[68:71], v[144:147], v[214:217], v[68:71]
	v_mfma_f32_16x16x32_bf16 v[64:67], v[160:163], v[214:217], v[64:67]
	s_setprio 0
	s_barrier
; #define PG8_STAGE(bufoff, gbase, voff) do { _Pragma("unroll") for (int _i = 0; _i < 2; ++_i) \
;         __builtin_amdgcn_global_load_lds((const unsigned*)((const char*)(gbase) + (voff)[_i]), (LAS unsigned*)(lds + (bufoff) + ldsw + _i * 8192), 16, 0, 0); } while (0)
; #define PG8_LDA(dst, b, h) do { _Pragma("unroll") for (int m = 0; m < 4; ++m) _Pragma("unroll") for (int k = 0; k < 2; ++k) dst[m][k] = *(const LAS bf16x8*)(lds + PG8_SA(b, h) + aoff + m * 2048 + k * 1024); } while (0)
; #define PG8_MMA(ai, bj, At, Bt) do { __builtin_amdgcn_s_setprio(1); _Pragma("unroll") for (int m = 0; m < 4; ++m) _Pragma("unroll") for (int n = 0; n < 2; ++n) _Pragma("unroll") for (int k = 0; k < 2; ++k) \
;         acc[ai][bj][m][n] = __builtin_amdgcn_mfma_f32_16x16x32_bf16(Bt[n][k], At[m][k], acc[ai][bj][m][n], 0, 0, 0); __builtin_amdgcn_s_setprio(0); } while (0)
; #define PG8_WAIT_V(n) asm volatile("s_waitcnt vmcnt(" #n ")" ::: "memory")
; #define PG8_WAIT_L(n) asm volatile("s_waitcnt lgkmcnt(" #n ")" ::: "memory")
; #define PG8_BAR __builtin_amdgcn_s_barrier()
; #define PG8_SCHED __builtin_amdgcn_sched_barrier(0)
; template <class Epi, bool ALIGN_EPI>
; __device__ __forceinline__ void gemm_phase(LAS unsigned char* lds, const Gemm g, int G, int cid, const Epi& E) {
;     ...
;             PG8_LDA(At, 1, 1); PG8_STAGE(PG8_SB(1, 0), b3, voffB); PG8_STAGE(PG8_SB(1, 1), b3 + hB, voffB); PG8_STAGE(PG8_SA(1, 0), a3, voffA);
;             PG8_WAIT_V(8); PG8_WAIT_L(0); PG8_BAR; PG8_MMA(1, 0, At, B0); PG8_MMA(1, 1, At, B1); PG8_BAR; PG8_SCHED;
	s_add_u32 s46, s48, 0x40000
	s_addc_u32 s47, s49, 0
	s_add_i32 s6, s6, s25
	v_lshl_add_u64 v[218:219], s[46:47], 0, v[138:139]
	s_mov_b32 m0, s6
	ds_read_b128 v[164:167], v222 offset:49152
	ds_read_b128 v[168:171], v222 offset:50176
	ds_read_b128 v[172:175], v222 offset:51200
	ds_read_b128 v[176:179], v222 offset:52224
	ds_read_b128 v[188:191], v222 offset:53248
	ds_read_b128 v[206:209], v222 offset:54272
	ds_read_b128 v[210:213], v222 offset:55296
	ds_read_b128 v[214:217], v222 offset:56320
	global_load_lds_dwordx4 v[218:219], off
	s_add_i32 m0, s6, 0x2000
	v_lshl_add_u64 v[218:219], s[46:47], 0, v[136:137]
	s_add_u32 s46, s48, 0x42000
	s_addc_u32 s47, s49, 0
	s_add_i32 s6, s7, s25
	global_load_lds_dwordx4 v[218:219], off
	v_lshl_add_u64 v[218:219], s[46:47], 0, v[138:139]
	s_mov_b32 m0, s6
	v_lshl_add_u64 v[198:199], v[198:199], 0, s[36:37]
	global_load_lds_dwordx4 v[218:219], off
	v_lshl_add_u64 v[218:219], s[46:47], 0, v[136:137]
	s_add_i32 m0, s6, 0x2000
	s_nop 0
	global_load_lds_dwordx4 v[218:219], off
	s_mov_b32 m0, s58
	s_nop 0
	global_load_lds_dwordx4 v[198:199], off
	v_lshl_add_u64 v[198:199], v[200:201], 0, s[36:37]
	s_mov_b32 m0, s59
	s_nop 0
	global_load_lds_dwordx4 v[198:199], off
	s_waitcnt vmcnt(9)
	s_waitcnt lgkmcnt(0)
	s_barrier
	s_setprio 1
	v_mfma_f32_16x16x32_bf16 v[60:63], v[112:115], v[164:167], v[60:63]
	v_mfma_f32_16x16x32_bf16 v[56:59], v[128:131], v[164:167], v[56:59]
	v_mfma_f32_16x16x32_bf16 v[44:47], v[112:115], v[172:175], v[44:47]
	v_mfma_f32_16x16x32_bf16 v[40:43], v[128:131], v[172:175], v[40:43]
	v_mfma_f32_16x16x32_bf16 v[28:31], v[112:115], v[188:191], v[28:31]
	v_mfma_f32_16x16x32_bf16 v[24:27], v[128:131], v[188:191], v[24:27]
	v_mfma_f32_16x16x32_bf16 v[12:15], v[112:115], v[210:213], v[12:15]
	v_mfma_f32_16x16x32_bf16 v[8:11], v[128:131], v[210:213], v[8:11]
	v_mfma_f32_16x16x32_bf16 v[60:63], v[116:119], v[168:171], v[60:63]
	v_mfma_f32_16x16x32_bf16 v[56:59], v[132:135], v[168:171], v[56:59]
	v_mfma_f32_16x16x32_bf16 v[44:47], v[116:119], v[176:179], v[44:47]
	v_mfma_f32_16x16x32_bf16 v[40:43], v[132:135], v[176:179], v[40:43]
	v_mfma_f32_16x16x32_bf16 v[28:31], v[116:119], v[206:209], v[28:31]
	v_mfma_f32_16x16x32_bf16 v[24:27], v[132:135], v[206:209], v[24:27]
	v_mfma_f32_16x16x32_bf16 v[12:15], v[116:119], v[214:217], v[12:15]
	v_mfma_f32_16x16x32_bf16 v[8:11], v[132:135], v[214:217], v[8:11]
	s_setprio 0
	s_setprio 1
	v_mfma_f32_16x16x32_bf16 v[52:55], v[140:143], v[164:167], v[52:55]
	v_mfma_f32_16x16x32_bf16 v[48:51], v[156:159], v[164:167], v[48:51]
	v_mfma_f32_16x16x32_bf16 v[36:39], v[140:143], v[172:175], v[36:39]
	v_mfma_f32_16x16x32_bf16 v[32:35], v[156:159], v[172:175], v[32:35]
	v_mfma_f32_16x16x32_bf16 v[20:23], v[140:143], v[188:191], v[20:23]
	v_mfma_f32_16x16x32_bf16 v[16:19], v[156:159], v[188:191], v[16:19]
	v_mfma_f32_16x16x32_bf16 v[4:7], v[140:143], v[210:213], v[4:7]
	v_mfma_f32_16x16x32_bf16 v[0:3], v[156:159], v[210:213], v[0:3]
	v_mfma_f32_16x16x32_bf16 v[52:55], v[144:147], v[168:171], v[52:55]
	v_mfma_f32_16x16x32_bf16 v[48:51], v[160:163], v[168:171], v[48:51]
	v_mfma_f32_16x16x32_bf16 v[36:39], v[144:147], v[176:179], v[36:39]
	v_mfma_f32_16x16x32_bf16 v[32:35], v[160:163], v[176:179], v[32:35]
	v_mfma_f32_16x16x32_bf16 v[20:23], v[144:147], v[206:209], v[20:23]
	v_mfma_f32_16x16x32_bf16 v[16:19], v[160:163], v[206:209], v[16:19]
	v_mfma_f32_16x16x32_bf16 v[4:7], v[144:147], v[214:217], v[4:7]
	v_mfma_f32_16x16x32_bf16 v[0:3], v[160:163], v[214:217], v[0:3]
	s_setprio 0
	s_barrier
	s_add_i32 s77, s77, 2
	s_add_u32 s75, s75, 0x80000
	s_addc_u32 s76, s76, 0
	s_cmp_gt_u32 s77, 29
	s_mov_b64 s[46:47], s[42:43]
	s_cbranch_scc0 .LBB0_727
; __device__ __forceinline__ unsigned cvt_pk_bf16(float lo, float hi) { unsigned r; asm volatile("v_cvt_pk_bf16_f32 %0, %1, %2" : "=v"(r) : "v"(lo), "v"(hi)); return r; }
;     __device__ __forceinline__ void operator()(const f32x4 (&acc)[2][2][4][2], const Unit& u, int wr, int wc, int fr, int fq, const LAS float*) const {
;     ...
;         for (int am = 0; am < NB; ++am) { const int ai = am / (NB / 2), m0 = (am % (NB / 2)) * MB;
;             f32x4 xo[4][2][2];
; #pragma unroll
;             for (int m = m0; m < m0 + MB; ++m) { const float* xr = Xs + (size_t)(row0 + ai * HALF + m * 16) * DM + col0;
; #pragma unroll
;                 for (int bj = 0; bj < 2; ++bj) { xo[m][bj][0] = *(const f32x4*)(xr + bj * HALF); xo[m][bj][1] = *(const f32x4*)(xr + bj * HALF + 4); } }
; #pragma unroll
;             for (int m = m0; m < m0 + MB; ++m) { const int row = row0 + ai * HALF + m * 16; float ss = 0.f;
;                 float* xr = X + (size_t)row * DM + col0; bf16_t* xb = XB + (size_t)row * ALD + col0;
; #pragma unroll
;                 for (int bj = 0; bj < 2; ++bj) { f32x4 x0 = xo[m][bj][0], x1 = xo[m][bj][1];
;                     if (HB) { x0 += (acc[ai][bj][m][0] + bv[bj][0]) * sv[bj][0]; x1 += (acc[ai][bj][m][1] + bv[bj][1]) * sv[bj][1]; } else { x0 += acc[ai][bj][m][0]; x1 += acc[ai][bj][m][1]; }
;                     *(f32x4*)(xr + bj * HALF) = x0; *(f32x4*)(xr + bj * HALF + 4) = x1;
;                     ss += (x0[0] * x0[0] + x0[1] * x0[1]) + (x0[2] * x0[2] + x0[3] * x0[3]) + (x1[0] * x1[0] + x1[1] * x1[1]) + (x1[2] * x1[2] + x1[3] * x1[3]);
;                     u32x4 w; w.x = cvt_pk_bf16(x0[0], x0[1]); w.y = cvt_pk_bf16(x0[2], x0[3]); w.z = cvt_pk_bf16(x1[0], x1[1]); w.w = cvt_pk_bf16(x1[2], x1[3]);
;                     if (feeds) *(u32x4*)(xb + bj * HALF) = w; }
;                 ss += __shfl_xor(ss, 16); ss += __shfl_xor(ss, 32);
;                 if (fq == 0 && feeds) part[(size_t)row * NPART + u.pn * 4 + wc] = ss; }
	v_lshl_or_b32 v188, s12, 8, v221
	v_lshl_add_u32 v190, s13, 8, v197
	v_ashrrev_i32_e32 v189, 31, v188
	v_lshlrev_b64 v[198:199], 2, v[188:189]
	v_ashrrev_i32_e32 v191, 31, v190
	v_lshl_add_u64 v[206:207], s[22:23], 0, v[198:199]
	v_lshlrev_b64 v[200:201], 13, v[190:191]
	v_lshl_add_u64 v[112:113], v[206:207], 0, v[200:201]
	global_load_dwordx4 v[224:227], v[112:113], off offset:16
	global_load_dwordx4 v[228:231], v[112:113], off
	global_load_dwordx4 v[232:235], v[112:113], off offset:528
	global_load_dwordx4 v[244:247], v[112:113], off offset:512
	v_or_b32_e32 v214, 16, v190
	v_ashrrev_i32_e32 v215, 31, v214
	v_or_b32_e32 v210, 32, v190
	v_or_b32_e32 v208, 48, v190
	v_lshlrev_b64 v[218:219], 13, v[214:215]
	v_ashrrev_i32_e32 v211, 31, v210
	v_ashrrev_i32_e32 v209, 31, v208
	v_lshl_add_u64 v[112:113], v[206:207], 0, v[218:219]
	v_lshlrev_b64 v[216:217], 13, v[210:211]
	v_lshlrev_b64 v[212:213], 13, v[208:209]
	global_load_dwordx4 v[172:175], v[112:113], off offset:16
	global_load_dwordx4 v[176:179], v[112:113], off
	global_load_dwordx4 v[164:167], v[112:113], off offset:528
	global_load_dwordx4 v[168:171], v[112:113], off offset:512
	v_lshl_add_u64 v[112:113], v[206:207], 0, v[216:217]
	v_lshl_add_u64 v[116:117], v[206:207], 0, v[212:213]
	global_load_dwordx4 v[156:159], v[112:113], off offset:16
	global_load_dwordx4 v[160:163], v[112:113], off
	global_load_dwordx4 v[128:131], v[112:113], off offset:528
	global_load_dwordx4 v[144:147], v[112:113], off offset:512
	global_load_dwordx4 v[132:135], v[116:117], off offset:16
	global_load_dwordx4 v[140:143], v[116:117], off
	s_nop 0
	global_load_dwordx4 v[112:115], v[116:117], off offset:528
	s_nop 0
	global_load_dwordx4 v[116:119], v[116:117], off offset:512
	v_lshl_add_u64 v[200:201], s[82:83], 0, v[200:201]
	v_lshl_add_u64 v[198:199], v[200:201], 0, v[198:199]
	v_mov_b64_e32 v[200:201], s[4:5]
	s_lshl_b32 s42, s12, 2
	v_mad_i64_i32 v[200:201], s[12:13], v190, s66, v[200:201]
	v_lshl_add_u64 v[200:201], v[188:189], 1, v[200:201]
	s_ashr_i32 s43, s42, 31
	s_waitcnt vmcnt(12)
	v_pk_add_f32 v[148:149], v[148:149], v[224:225]
	v_pk_add_f32 v[154:155], v[154:155], v[230:231]
	v_pk_add_f32 v[152:153], v[152:153], v[228:229]
	v_mul_f32_e32 v224, v155, v155
	v_mul_f32_e32 v223, v153, v153
	v_fmac_f32_e32 v223, v152, v152
	v_fmac_f32_e32 v224, v154, v154
	v_add_f32_e32 v223, v223, v224
	v_mul_f32_e32 v224, v149, v149
	v_pk_add_f32 v[126:127], v[126:127], v[246:247]
	v_pk_add_f32 v[124:125], v[124:125], v[244:245]
	v_pk_add_f32 v[150:151], v[150:151], v[226:227]
	global_store_dwordx4 v[198:199], v[152:155], off
	global_store_dwordx4 v[198:199], v[148:151], off offset:16
	v_fmac_f32_e32 v224, v148, v148
	v_cvt_pk_bf16_f32 v152, v152, v153
	v_cvt_pk_bf16_f32 v153, v154, v155
	v_cvt_pk_bf16_f32 v154, v148, v149
	v_pk_add_f32 v[120:121], v[120:121], v[232:233]
	v_mul_f32_e32 v148, v125, v125
	v_mul_f32_e32 v149, v127, v127
	v_fmac_f32_e32 v148, v124, v124
	v_fmac_f32_e32 v149, v126, v126
	v_add_f32_e32 v148, v148, v149
	v_mul_f32_e32 v149, v121, v121
	v_cvt_pk_bf16_f32 v155, v150, v151
	global_store_dwordx4 v[200:201], v[152:155], off
	v_pk_add_f32 v[122:123], v[122:123], v[234:235]
	global_store_dwordx4 v[198:199], v[124:127], off offset:512
	global_store_dwordx4 v[198:199], v[120:123], off offset:528
	v_fmac_f32_e32 v149, v120, v120
	v_cvt_pk_bf16_f32 v124, v124, v125
	v_cvt_pk_bf16_f32 v125, v126, v127
	v_cvt_pk_bf16_f32 v126, v120, v121
	v_add_f32_e32 v223, v223, v224
	v_and_b32_e32 v121, 64, v239
	v_mul_f32_e32 v224, v151, v151
	v_add_f32_e32 v148, v148, v149
	v_mul_f32_e32 v149, v123, v123
	v_xor_b32_e32 v120, 16, v239
	v_add_u32_e32 v121, 64, v121
	v_fmac_f32_e32 v224, v150, v150
	v_fmac_f32_e32 v149, v122, v122
	v_cmp_lt_i32_e32 vcc, v120, v121
	v_add_f32_e32 v223, v224, v223
	v_add_f32_e32 v148, v149, v148
	v_cndmask_b32_e32 v120, v239, v120, vcc
	v_add_f32_e32 v148, v223, v148
	v_cvt_pk_bf16_f32 v127, v122, v123
	global_store_dwordx4 v[200:201], v[124:127], off offset:256
	v_xor_b32_e32 v122, 32, v239
	v_cmp_lt_i32_e32 vcc, v122, v121
	v_lshlrev_b32_e32 v126, 2, v120
	ds_bpermute_b32 v120, v126, v148
	v_cndmask_b32_e32 v121, v239, v122, vcc
	v_lshlrev_b32_e32 v127, 2, v121
	s_waitcnt lgkmcnt(0)
	v_add_f32_e32 v120, v148, v120
	ds_bpermute_b32 v121, v127, v120
	s_and_saveexec_b64 s[46:47], s[38:39]
	s_cbranch_execz .LBB0_730
	v_lshlrev_b64 v[122:123], 7, v[190:191]
	v_lshl_add_u64 v[122:123], s[94:95], 0, v[122:123]
	v_lshl_add_u64 v[122:123], s[42:43], 2, v[122:123]
	s_lshl_b32 s30, s57, 2
	v_lshl_add_u64 v[122:123], v[122:123], 0, s[30:31]
	s_waitcnt lgkmcnt(0)
	v_add_f32_e32 v120, v120, v121
	global_store_dword v[122:123], v120, off

; #define PG8_STAGE(bufoff, gbase, voff) do { _Pragma("unroll") for (int _i = 0; _i < 2; ++_i) \
;         __builtin_amdgcn_global_load_lds((const unsigned*)((const char*)(gbase) + (voff)[_i]), (LAS unsigned*)(lds + (bufoff) + ldsw + _i * 8192), 16, 0, 0); } while (0)
; #define PG8_LDA(dst, b, h) do { _Pragma("unroll") for (int m = 0; m < 4; ++m) _Pragma("unroll") for (int k = 0; k < 2; ++k) dst[m][k] = *(const LAS bf16x8*)(lds + PG8_SA(b, h) + aoff + m * 2048 + k * 1024); } while (0)
; #define PG8_LDB(dst, b, h) do { _Pragma("unroll") for (int n = 0; n < 2; ++n) _Pragma("unroll") for (int k = 0; k < 2; ++k) dst[n][k] = *(const LAS bf16x8*)(lds + PG8_SB(b, h) + boff + n * 2048 + k * 1024); } while (0)
; #define PG8_MMA(ai, bj, At, Bt) do { __builtin_amdgcn_s_setprio(1); _Pragma("unroll") for (int m = 0; m < 4; ++m) _Pragma("unroll") for (int n = 0; n < 2; ++n) _Pragma("unroll") for (int k = 0; k < 2; ++k) \
;         acc[ai][bj][m][n] = __builtin_amdgcn_mfma_f32_16x16x32_bf16(Bt[n][k], At[m][k], acc[ai][bj][m][n], 0, 0, 0); __builtin_amdgcn_s_setprio(0); } while (0)
; #define PG8_WAIT_V(n) asm volatile("s_waitcnt vmcnt(" #n ")" ::: "memory")
; #define PG8_WAIT_L(n) asm volatile("s_waitcnt lgkmcnt(" #n ")" ::: "memory")
; #define PG8_BAR __builtin_amdgcn_s_barrier()
; #define PG8_SCHED __builtin_amdgcn_sched_barrier(0)
; template <class Epi, bool ALIGN_EPI>
; __device__ __forceinline__ void gemm_phase(LAS unsigned char* lds, const Gemm g, int G, int cid, const Epi& E) {
;     ...
;             PG8_LDB(B0, 0, 0); PG8_LDB(B1, 0, 1); PG8_SCHED; PG8_LDA(At, 0, 0); PG8_STAGE(PG8_SA(1, 1), a1 + hA, voffA);
;             PG8_WAIT_V(8); PG8_WAIT_L(0); PG8_BAR; PG8_MMA(0, 0, At, B0); PG8_MMA(0, 1, At, B1); PG8_BAR; PG8_SCHED;
;             PG8_LDA(At, 0, 1); PG8_STAGE(PG8_SB(0, 0), b2, voffB); PG8_STAGE(PG8_SB(0, 1), b2 + hB, voffB); PG8_STAGE(PG8_SA(0, 0), a2, voffA);
;             PG8_WAIT_V(8); PG8_WAIT_L(0); PG8_BAR; PG8_MMA(1, 0, At, B0); PG8_MMA(1, 1, At, B1); PG8_BAR; PG8_SCHED;
.LBB0_813:
	s_add_u32 s54, s52, 0x100
	s_addc_u32 s55, s53, 0
	s_and_b64 s[6:7], exec, s[58:59]
	s_cselect_b32 s59, s45, s55
	s_cselect_b32 s58, s44, s54
	s_add_i32 s6, 0, 0x10000
	s_add_i32 s92, 0, 0x14000
	v_add_u32_e32 v144, s6, v176
	v_add_u32_e32 v160, s92, v176
	ds_read_b128 v[128:131], v144
	ds_read_b128 v[132:135], v144 offset:1024
	ds_read_b128 v[140:143], v144 offset:2048
	ds_read_b128 v[144:147], v144 offset:3072
	ds_read_b128 v[148:151], v160
	ds_read_b128 v[152:155], v160 offset:1024
	ds_read_b128 v[156:159], v160 offset:2048
	ds_read_b128 v[160:163], v160 offset:3072
	v_lshl_add_u64 v[198:199], s[52:53], 0, v[170:171]
	s_add_i32 m0, s13, 0xc000
	ds_read_b128 v[180:183], v179
	ds_read_b128 v[184:187], v179 offset:1024
	ds_read_b128 v[188:191], v179 offset:2048
	ds_read_b128 v[206:209], v179 offset:3072
	ds_read_b128 v[210:213], v179 offset:4096
	ds_read_b128 v[214:217], v179 offset:5120
	ds_read_b128 v[218:221], v179 offset:6144
	ds_read_b128 v[222:225], v179 offset:7168
	global_load_lds_dwordx4 v[198:199], off
	v_lshl_add_u64 v[198:199], s[52:53], 0, v[172:173]
	s_add_i32 m0, s13, 0xe000
	s_nop 0
	global_load_lds_dwordx4 v[198:199], off
	s_waitcnt vmcnt(8)
	s_waitcnt lgkmcnt(0)
	s_barrier
	s_setprio 1
	v_mfma_f32_16x16x32_bf16 v[124:127], v[128:131], v[180:183], v[124:127]
	v_mfma_f32_16x16x32_bf16 v[120:123], v[140:143], v[180:183], v[120:123]
	v_mfma_f32_16x16x32_bf16 v[108:111], v[128:131], v[188:191], v[108:111]
	v_mfma_f32_16x16x32_bf16 v[104:107], v[140:143], v[188:191], v[104:107]
	v_mfma_f32_16x16x32_bf16 v[92:95], v[128:131], v[210:213], v[92:95]
	v_mfma_f32_16x16x32_bf16 v[88:91], v[140:143], v[210:213], v[88:91]
	v_mfma_f32_16x16x32_bf16 v[76:79], v[128:131], v[218:221], v[76:79]
	v_mfma_f32_16x16x32_bf16 v[72:75], v[140:143], v[218:221], v[72:75]
	v_mfma_f32_16x16x32_bf16 v[124:127], v[132:135], v[184:187], v[124:127]
	v_mfma_f32_16x16x32_bf16 v[120:123], v[144:147], v[184:187], v[120:123]
	v_mfma_f32_16x16x32_bf16 v[108:111], v[132:135], v[206:209], v[108:111]
	v_mfma_f32_16x16x32_bf16 v[104:107], v[144:147], v[206:209], v[104:107]
	v_mfma_f32_16x16x32_bf16 v[92:95], v[132:135], v[214:217], v[92:95]
	v_mfma_f32_16x16x32_bf16 v[88:91], v[144:147], v[214:217], v[88:91]
	v_mfma_f32_16x16x32_bf16 v[76:79], v[132:135], v[222:225], v[76:79]
	v_mfma_f32_16x16x32_bf16 v[72:75], v[144:147], v[222:225], v[72:75]
	s_setprio 0
	s_setprio 1
	v_mfma_f32_16x16x32_bf16 v[116:119], v[148:151], v[180:183], v[116:119]
	v_mfma_f32_16x16x32_bf16 v[112:115], v[156:159], v[180:183], v[112:115]
	v_mfma_f32_16x16x32_bf16 v[100:103], v[148:151], v[188:191], v[100:103]
	v_mfma_f32_16x16x32_bf16 v[96:99], v[156:159], v[188:191], v[96:99]
	v_mfma_f32_16x16x32_bf16 v[84:87], v[148:151], v[210:213], v[84:87]
	v_mfma_f32_16x16x32_bf16 v[80:83], v[156:159], v[210:213], v[80:83]
	v_mfma_f32_16x16x32_bf16 v[68:71], v[148:151], v[218:221], v[68:71]
	v_mfma_f32_16x16x32_bf16 v[64:67], v[156:159], v[218:221], v[64:67]
	v_mfma_f32_16x16x32_bf16 v[116:119], v[152:155], v[184:187], v[116:119]
	v_mfma_f32_16x16x32_bf16 v[112:115], v[160:163], v[184:187], v[112:115]
	v_mfma_f32_16x16x32_bf16 v[100:103], v[152:155], v[206:209], v[100:103]
	v_mfma_f32_16x16x32_bf16 v[96:99], v[160:163], v[206:209], v[96:99]
	v_mfma_f32_16x16x32_bf16 v[84:87], v[152:155], v[214:217], v[84:87]
	v_mfma_f32_16x16x32_bf16 v[80:83], v[160:163], v[214:217], v[80:83]
	v_mfma_f32_16x16x32_bf16 v[68:71], v[152:155], v[222:225], v[68:71]
	v_mfma_f32_16x16x32_bf16 v[64:67], v[160:163], v[222:225], v[64:67]
	s_setprio 0
	s_barrier
	s_add_i32 s6, s6, s12
	v_lshl_add_u64 v[198:199], s[56:57], 0, v[164:165]
	s_mov_b32 m0, s6
	ds_read_b128 v[180:183], v179 offset:16384
	ds_read_b128 v[184:187], v179 offset:17408
	ds_read_b128 v[188:191], v179 offset:18432
	ds_read_b128 v[206:209], v179 offset:19456
	ds_read_b128 v[210:213], v179 offset:20480
	ds_read_b128 v[214:217], v179 offset:21504
	ds_read_b128 v[218:221], v179 offset:22528
	ds_read_b128 v[222:225], v179 offset:23552
	global_load_lds_dwordx4 v[198:199], off
	s_add_i32 m0, s6, 0x2000
	s_add_u32 s6, s56, 0x2000
	v_lshl_add_u64 v[198:199], s[56:57], 0, v[168:169]
	s_addc_u32 s7, s57, 0
	s_add_i32 s52, s92, s12
	global_load_lds_dwordx4 v[198:199], off
	v_lshl_add_u64 v[198:199], s[6:7], 0, v[164:165]
	s_mov_b32 m0, s52
	v_lshl_add_u64 v[200:201], s[58:59], 0, v[166:167]
	global_load_lds_dwordx4 v[198:199], off
	v_lshl_add_u64 v[198:199], s[6:7], 0, v[168:169]
	s_add_i32 m0, s52, 0x2000
	s_nop 0
	global_load_lds_dwordx4 v[198:199], off
	v_lshl_add_u64 v[198:199], s[58:59], 0, v[136:137]
	s_mov_b32 m0, s13
	s_nop 0
	global_load_lds_dwordx4 v[198:199], off
	s_mov_b32 m0, s24
	s_nop 0
	global_load_lds_dwordx4 v[200:201], off
	s_waitcnt vmcnt(8)
	s_waitcnt lgkmcnt(0)
	s_barrier
; #define PG8_STAGE(bufoff, gbase, voff) do { _Pragma("unroll") for (int _i = 0; _i < 2; ++_i) \
;         __builtin_amdgcn_global_load_lds((const unsigned*)((const char*)(gbase) + (voff)[_i]), (LAS unsigned*)(lds + (bufoff) + ldsw + _i * 8192), 16, 0, 0); } while (0)
; #define PG8_LDA(dst, b, h) do { _Pragma("unroll") for (int m = 0; m < 4; ++m) _Pragma("unroll") for (int k = 0; k < 2; ++k) dst[m][k] = *(const LAS bf16x8*)(lds + PG8_SA(b, h) + aoff + m * 2048 + k * 1024); } while (0)
; #define PG8_LDB(dst, b, h) do { _Pragma("unroll") for (int n = 0; n < 2; ++n) _Pragma("unroll") for (int k = 0; k < 2; ++k) dst[n][k] = *(const LAS bf16x8*)(lds + PG8_SB(b, h) + boff + n * 2048 + k * 1024); } while (0)
; #define PG8_MMA(ai, bj, At, Bt) do { __builtin_amdgcn_s_setprio(1); _Pragma("unroll") for (int m = 0; m < 4; ++m) _Pragma("unroll") for (int n = 0; n < 2; ++n) _Pragma("unroll") for (int k = 0; k < 2; ++k) \
;         acc[ai][bj][m][n] = __builtin_amdgcn_mfma_f32_16x16x32_bf16(Bt[n][k], At[m][k], acc[ai][bj][m][n], 0, 0, 0); __builtin_amdgcn_s_setprio(0); } while (0)
; #define PG8_WAIT_V(n) asm volatile("s_waitcnt vmcnt(" #n ")" ::: "memory")
; #define PG8_WAIT_L(n) asm volatile("s_waitcnt lgkmcnt(" #n ")" ::: "memory")
; #define PG8_BAR __builtin_amdgcn_s_barrier()
; #define PG8_SCHED __builtin_amdgcn_sched_barrier(0)
; template <class Epi, bool ALIGN_EPI>
; __device__ __forceinline__ void gemm_phase(LAS unsigned char* lds, const Gemm g, int G, int cid, const Epi& E) {
;     ...
;             PG8_WAIT_V(8); PG8_WAIT_L(0); PG8_BAR; PG8_MMA(1, 0, At, B0); PG8_MMA(1, 1, At, B1); PG8_BAR; PG8_SCHED;
;             PG8_LDB(B0, 1, 0); PG8_LDB(B1, 1, 1); PG8_SCHED; PG8_LDA(At, 1, 0); PG8_STAGE(PG8_SA(0, 1), a2 + hA, voffA);
;             PG8_WAIT_V(8); PG8_WAIT_L(0); PG8_BAR; PG8_MMA(0, 0, At, B0); PG8_MMA(0, 1, At, B1); PG8_BAR; PG8_SCHED;
	s_setprio 1
	v_mfma_f32_16x16x32_bf16 v[60:63], v[128:131], v[180:183], v[60:63]
	v_mfma_f32_16x16x32_bf16 v[56:59], v[140:143], v[180:183], v[56:59]
	v_mfma_f32_16x16x32_bf16 v[44:47], v[128:131], v[188:191], v[44:47]
	v_mfma_f32_16x16x32_bf16 v[40:43], v[140:143], v[188:191], v[40:43]
	v_mfma_f32_16x16x32_bf16 v[28:31], v[128:131], v[210:213], v[28:31]
	v_mfma_f32_16x16x32_bf16 v[24:27], v[140:143], v[210:213], v[24:27]
	v_mfma_f32_16x16x32_bf16 v[12:15], v[128:131], v[218:221], v[12:15]
	v_mfma_f32_16x16x32_bf16 v[8:11], v[140:143], v[218:221], v[8:11]
	v_mfma_f32_16x16x32_bf16 v[60:63], v[132:135], v[184:187], v[60:63]
	v_mfma_f32_16x16x32_bf16 v[56:59], v[144:147], v[184:187], v[56:59]
	v_mfma_f32_16x16x32_bf16 v[44:47], v[132:135], v[206:209], v[44:47]
	v_mfma_f32_16x16x32_bf16 v[40:43], v[144:147], v[206:209], v[40:43]
	v_mfma_f32_16x16x32_bf16 v[28:31], v[132:135], v[214:217], v[28:31]
	v_mfma_f32_16x16x32_bf16 v[24:27], v[144:147], v[214:217], v[24:27]
	v_mfma_f32_16x16x32_bf16 v[12:15], v[132:135], v[222:225], v[12:15]
	v_mfma_f32_16x16x32_bf16 v[8:11], v[144:147], v[222:225], v[8:11]
	s_setprio 0
	s_setprio 1
	v_mfma_f32_16x16x32_bf16 v[52:55], v[148:151], v[180:183], v[52:55]
	v_mfma_f32_16x16x32_bf16 v[48:51], v[156:159], v[180:183], v[48:51]
	v_mfma_f32_16x16x32_bf16 v[36:39], v[148:151], v[188:191], v[36:39]
	v_mfma_f32_16x16x32_bf16 v[32:35], v[156:159], v[188:191], v[32:35]
	v_mfma_f32_16x16x32_bf16 v[20:23], v[148:151], v[210:213], v[20:23]
	v_mfma_f32_16x16x32_bf16 v[16:19], v[156:159], v[210:213], v[16:19]
	v_mfma_f32_16x16x32_bf16 v[4:7], v[148:151], v[218:221], v[4:7]
	v_mfma_f32_16x16x32_bf16 v[0:3], v[156:159], v[218:221], v[0:3]
	v_mfma_f32_16x16x32_bf16 v[52:55], v[152:155], v[184:187], v[52:55]
	v_mfma_f32_16x16x32_bf16 v[48:51], v[160:163], v[184:187], v[48:51]
	v_mfma_f32_16x16x32_bf16 v[36:39], v[152:155], v[206:209], v[36:39]
	v_mfma_f32_16x16x32_bf16 v[32:35], v[160:163], v[206:209], v[32:35]
	v_mfma_f32_16x16x32_bf16 v[20:23], v[152:155], v[214:217], v[20:23]
	v_mfma_f32_16x16x32_bf16 v[16:19], v[160:163], v[214:217], v[16:19]
	v_mfma_f32_16x16x32_bf16 v[4:7], v[152:155], v[222:225], v[4:7]
	v_mfma_f32_16x16x32_bf16 v[0:3], v[160:163], v[222:225], v[0:3]
	s_setprio 0
	s_barrier
	s_add_i32 s52, 0, 0x18000
	s_add_i32 s53, 0, 0x1c000
	v_add_u32_e32 v144, s52, v176
	v_add_u32_e32 v160, s53, v176
	ds_read_b128 v[128:131], v144
	ds_read_b128 v[132:135], v144 offset:1024
	ds_read_b128 v[140:143], v144 offset:2048
	ds_read_b128 v[144:147], v144 offset:3072
	ds_read_b128 v[148:151], v160
	ds_read_b128 v[152:155], v160 offset:1024
	ds_read_b128 v[156:159], v160 offset:2048
	ds_read_b128 v[160:163], v160 offset:3072
	s_add_u32 s6, s58, 0x84000
	s_addc_u32 s7, s59, 0
	s_mov_b32 m0, s25
	v_lshl_add_u64 v[226:227], s[6:7], 0, v[136:137]
	ds_read_b128 v[180:183], v179 offset:32768
	ds_read_b128 v[184:187], v179 offset:33792
	ds_read_b128 v[188:191], v179 offset:34816
	ds_read_b128 v[206:209], v179 offset:35840
	ds_read_b128 v[210:213], v179 offset:36864
	ds_read_b128 v[214:217], v179 offset:37888
	ds_read_b128 v[218:221], v179 offset:38912
	ds_read_b128 v[222:225], v179 offset:39936
	global_load_lds_dwordx4 v[226:227], off
	v_lshl_add_u64 v[226:227], s[6:7], 0, v[166:167]
	s_mov_b32 m0, s74
	s_nop 0
	global_load_lds_dwordx4 v[226:227], off
	s_waitcnt vmcnt(8)
	s_waitcnt lgkmcnt(0)
	s_barrier
	s_setprio 1
	v_mfma_f32_16x16x32_bf16 v[124:127], v[128:131], v[180:183], v[124:127]
	v_mfma_f32_16x16x32_bf16 v[120:123], v[140:143], v[180:183], v[120:123]
	v_mfma_f32_16x16x32_bf16 v[108:111], v[128:131], v[188:191], v[108:111]
	v_mfma_f32_16x16x32_bf16 v[104:107], v[140:143], v[188:191], v[104:107]
	v_mfma_f32_16x16x32_bf16 v[92:95], v[128:131], v[210:213], v[92:95]
	v_mfma_f32_16x16x32_bf16 v[88:91], v[140:143], v[210:213], v[88:91]
	v_mfma_f32_16x16x32_bf16 v[76:79], v[128:131], v[218:221], v[76:79]
	v_mfma_f32_16x16x32_bf16 v[72:75], v[140:143], v[218:221], v[72:75]
	v_mfma_f32_16x16x32_bf16 v[124:127], v[132:135], v[184:187], v[124:127]
	v_mfma_f32_16x16x32_bf16 v[120:123], v[144:147], v[184:187], v[120:123]
	v_mfma_f32_16x16x32_bf16 v[108:111], v[132:135], v[206:209], v[108:111]
	v_mfma_f32_16x16x32_bf16 v[104:107], v[144:147], v[206:209], v[104:107]
	v_mfma_f32_16x16x32_bf16 v[92:95], v[132:135], v[214:217], v[92:95]
	v_mfma_f32_16x16x32_bf16 v[88:91], v[144:147], v[214:217], v[88:91]
	v_mfma_f32_16x16x32_bf16 v[76:79], v[132:135], v[222:225], v[76:79]
	v_mfma_f32_16x16x32_bf16 v[72:75], v[144:147], v[222:225], v[72:75]
	s_setprio 0
	s_setprio 1
	v_mfma_f32_16x16x32_bf16 v[116:119], v[148:151], v[180:183], v[116:119]
	v_mfma_f32_16x16x32_bf16 v[112:115], v[156:159], v[180:183], v[112:115]
	v_mfma_f32_16x16x32_bf16 v[100:103], v[148:151], v[188:191], v[100:103]
	v_mfma_f32_16x16x32_bf16 v[96:99], v[156:159], v[188:191], v[96:99]
	v_mfma_f32_16x16x32_bf16 v[84:87], v[148:151], v[210:213], v[84:87]
	v_mfma_f32_16x16x32_bf16 v[80:83], v[156:159], v[210:213], v[80:83]
	v_mfma_f32_16x16x32_bf16 v[68:71], v[148:151], v[218:221], v[68:71]
	v_mfma_f32_16x16x32_bf16 v[64:67], v[156:159], v[218:221], v[64:67]
	v_mfma_f32_16x16x32_bf16 v[116:119], v[152:155], v[184:187], v[116:119]
	v_mfma_f32_16x16x32_bf16 v[112:115], v[160:163], v[184:187], v[112:115]
	v_mfma_f32_16x16x32_bf16 v[100:103], v[152:155], v[206:209], v[100:103]
	v_mfma_f32_16x16x32_bf16 v[96:99], v[160:163], v[206:209], v[96:99]
	v_mfma_f32_16x16x32_bf16 v[84:87], v[152:155], v[214:217], v[84:87]
	v_mfma_f32_16x16x32_bf16 v[80:83], v[160:163], v[214:217], v[80:83]
	v_mfma_f32_16x16x32_bf16 v[68:71], v[152:155], v[222:225], v[68:71]
	v_mfma_f32_16x16x32_bf16 v[64:67], v[160:163], v[222:225], v[64:67]
	s_setprio 0
	s_barrier
; #define PG8_STAGE(bufoff, gbase, voff) do { _Pragma("unroll") for (int _i = 0; _i < 2; ++_i) \
;         __builtin_amdgcn_global_load_lds((const unsigned*)((const char*)(gbase) + (voff)[_i]), (LAS unsigned*)(lds + (bufoff) + ldsw + _i * 8192), 16, 0, 0); } while (0)
; #define PG8_LDA(dst, b, h) do { _Pragma("unroll") for (int m = 0; m < 4; ++m) _Pragma("unroll") for (int k = 0; k < 2; ++k) dst[m][k] = *(const LAS bf16x8*)(lds + PG8_SA(b, h) + aoff + m * 2048 + k * 1024); } while (0)
; #define PG8_MMA(ai, bj, At, Bt) do { __builtin_amdgcn_s_setprio(1); _Pragma("unroll") for (int m = 0; m < 4; ++m) _Pragma("unroll") for (int n = 0; n < 2; ++n) _Pragma("unroll") for (int k = 0; k < 2; ++k) \
;         acc[ai][bj][m][n] = __builtin_amdgcn_mfma_f32_16x16x32_bf16(Bt[n][k], At[m][k], acc[ai][bj][m][n], 0, 0, 0); __builtin_amdgcn_s_setprio(0); } while (0)
; #define PG8_WAIT_V(n) asm volatile("s_waitcnt vmcnt(" #n ")" ::: "memory")
; #define PG8_WAIT_L(n) asm volatile("s_waitcnt lgkmcnt(" #n ")" ::: "memory")
; #define PG8_BAR __builtin_amdgcn_s_barrier()
; #define PG8_SCHED __builtin_amdgcn_sched_barrier(0)
; template <class Epi, bool ALIGN_EPI>
; __device__ __forceinline__ void gemm_phase(LAS unsigned char* lds, const Gemm g, int G, int cid, const Epi& E) {
;     ...
;             PG8_LDA(At, 1, 1); PG8_STAGE(PG8_SB(1, 0), b3, voffB); PG8_STAGE(PG8_SB(1, 1), b3 + hB, voffB); PG8_STAGE(PG8_SA(1, 0), a3, voffA);
;             PG8_WAIT_V(8); PG8_WAIT_L(0); PG8_BAR; PG8_MMA(1, 0, At, B0); PG8_MMA(1, 1, At, B1); PG8_BAR; PG8_SCHED;
	s_add_u32 s6, s56, 0x160000
	s_addc_u32 s7, s57, 0
	s_add_i32 s52, s52, s12
	v_lshl_add_u64 v[226:227], s[6:7], 0, v[164:165]
	s_mov_b32 m0, s52
	ds_read_b128 v[180:183], v179 offset:49152
	ds_read_b128 v[184:187], v179 offset:50176
	ds_read_b128 v[188:191], v179 offset:51200
	ds_read_b128 v[206:209], v179 offset:52224
	ds_read_b128 v[210:213], v179 offset:53248
	ds_read_b128 v[214:217], v179 offset:54272
	ds_read_b128 v[218:221], v179 offset:55296
	ds_read_b128 v[222:225], v179 offset:56320
	global_load_lds_dwordx4 v[226:227], off
	s_add_i32 m0, s52, 0x2000
	v_lshl_add_u64 v[226:227], s[6:7], 0, v[168:169]
	s_add_u32 s6, s56, 0x162000
	s_addc_u32 s7, s57, 0
	s_add_i32 s52, s53, s12
	global_load_lds_dwordx4 v[226:227], off
	v_lshl_add_u64 v[226:227], s[6:7], 0, v[164:165]
	s_mov_b32 m0, s52
	v_lshl_add_u64 v[198:199], v[198:199], 0, s[36:37]
	global_load_lds_dwordx4 v[226:227], off
	v_lshl_add_u64 v[226:227], s[6:7], 0, v[168:169]
	s_add_i32 m0, s52, 0x2000
	s_nop 0
	global_load_lds_dwordx4 v[226:227], off
	s_mov_b32 m0, s75
	s_nop 0
	global_load_lds_dwordx4 v[198:199], off
	v_lshl_add_u64 v[198:199], v[200:201], 0, s[36:37]
	s_mov_b32 m0, s76
	s_nop 0
	global_load_lds_dwordx4 v[198:199], off
	s_waitcnt vmcnt(8)
	s_waitcnt lgkmcnt(0)
	s_barrier
	s_setprio 1
	v_mfma_f32_16x16x32_bf16 v[60:63], v[128:131], v[180:183], v[60:63]
	v_mfma_f32_16x16x32_bf16 v[56:59], v[140:143], v[180:183], v[56:59]
	v_mfma_f32_16x16x32_bf16 v[44:47], v[128:131], v[188:191], v[44:47]
	v_mfma_f32_16x16x32_bf16 v[40:43], v[140:143], v[188:191], v[40:43]
	v_mfma_f32_16x16x32_bf16 v[28:31], v[128:131], v[210:213], v[28:31]
	v_mfma_f32_16x16x32_bf16 v[24:27], v[140:143], v[210:213], v[24:27]
	v_mfma_f32_16x16x32_bf16 v[12:15], v[128:131], v[218:221], v[12:15]
	v_mfma_f32_16x16x32_bf16 v[8:11], v[140:143], v[218:221], v[8:11]
	v_mfma_f32_16x16x32_bf16 v[60:63], v[132:135], v[184:187], v[60:63]
	v_mfma_f32_16x16x32_bf16 v[56:59], v[144:147], v[184:187], v[56:59]
	v_mfma_f32_16x16x32_bf16 v[44:47], v[132:135], v[206:209], v[44:47]
	v_mfma_f32_16x16x32_bf16 v[40:43], v[144:147], v[206:209], v[40:43]
	v_mfma_f32_16x16x32_bf16 v[28:31], v[132:135], v[214:217], v[28:31]
	v_mfma_f32_16x16x32_bf16 v[24:27], v[144:147], v[214:217], v[24:27]
	v_mfma_f32_16x16x32_bf16 v[12:15], v[132:135], v[222:225], v[12:15]
	v_mfma_f32_16x16x32_bf16 v[8:11], v[144:147], v[222:225], v[8:11]
	s_setprio 0
	s_setprio 1
	v_mfma_f32_16x16x32_bf16 v[52:55], v[148:151], v[180:183], v[52:55]
	v_mfma_f32_16x16x32_bf16 v[48:51], v[156:159], v[180:183], v[48:51]
	v_mfma_f32_16x16x32_bf16 v[36:39], v[148:151], v[188:191], v[36:39]
	v_mfma_f32_16x16x32_bf16 v[32:35], v[156:159], v[188:191], v[32:35]
	v_mfma_f32_16x16x32_bf16 v[20:23], v[148:151], v[210:213], v[20:23]
	v_mfma_f32_16x16x32_bf16 v[16:19], v[156:159], v[210:213], v[16:19]
	v_mfma_f32_16x16x32_bf16 v[4:7], v[148:151], v[218:221], v[4:7]
	v_mfma_f32_16x16x32_bf16 v[0:3], v[156:159], v[218:221], v[0:3]
	v_mfma_f32_16x16x32_bf16 v[52:55], v[152:155], v[184:187], v[52:55]
	v_mfma_f32_16x16x32_bf16 v[48:51], v[160:163], v[184:187], v[48:51]
	v_mfma_f32_16x16x32_bf16 v[36:39], v[152:155], v[206:209], v[36:39]
	v_mfma_f32_16x16x32_bf16 v[32:35], v[160:163], v[206:209], v[32:35]
	v_mfma_f32_16x16x32_bf16 v[20:23], v[152:155], v[214:217], v[20:23]
	v_mfma_f32_16x16x32_bf16 v[16:19], v[160:163], v[214:217], v[16:19]
	v_mfma_f32_16x16x32_bf16 v[4:7], v[152:155], v[222:225], v[4:7]
	v_mfma_f32_16x16x32_bf16 v[0:3], v[160:163], v[222:225], v[0:3]
	s_setprio 0
	s_barrier
	s_add_i32 s91, s91, 2
	s_add_u32 s50, s50, 0x2c0000
	s_addc_u32 s51, s51, 0
	s_cmp_gt_u32 s91, 29
	s_mov_b64 s[52:53], s[54:55]
	s_cbranch_scc1 .LBB0_816

; #define PG8_STAGE(bufoff, gbase, voff) do { _Pragma("unroll") for (int _i = 0; _i < 2; ++_i) \
;         __builtin_amdgcn_global_load_lds((const unsigned*)((const char*)(gbase) + (voff)[_i]), (LAS unsigned*)(lds + (bufoff) + ldsw + _i * 8192), 16, 0, 0); } while (0)
; #define PG8_LDA(dst, b, h) do { _Pragma("unroll") for (int m = 0; m < 4; ++m) _Pragma("unroll") for (int k = 0; k < 2; ++k) dst[m][k] = *(const LAS bf16x8*)(lds + PG8_SA(b, h) + aoff + m * 2048 + k * 1024); } while (0)
; #define PG8_LDB(dst, b, h) do { _Pragma("unroll") for (int n = 0; n < 2; ++n) _Pragma("unroll") for (int k = 0; k < 2; ++k) dst[n][k] = *(const LAS bf16x8*)(lds + PG8_SB(b, h) + boff + n * 2048 + k * 1024); } while (0)
; #define PG8_MMA(ai, bj, At, Bt) do { __builtin_amdgcn_s_setprio(1); _Pragma("unroll") for (int m = 0; m < 4; ++m) _Pragma("unroll") for (int n = 0; n < 2; ++n) _Pragma("unroll") for (int k = 0; k < 2; ++k) \
;         acc[ai][bj][m][n] = __builtin_amdgcn_mfma_f32_16x16x32_bf16(Bt[n][k], At[m][k], acc[ai][bj][m][n], 0, 0, 0); __builtin_amdgcn_s_setprio(0); } while (0)
; #define PG8_WAIT_V(n) asm volatile("s_waitcnt vmcnt(" #n ")" ::: "memory")
; #define PG8_WAIT_L(n) asm volatile("s_waitcnt lgkmcnt(" #n ")" ::: "memory")
; #define PG8_BAR __builtin_amdgcn_s_barrier()
; #define PG8_SCHED __builtin_amdgcn_sched_barrier(0)
; template <class Epi, bool ALIGN_EPI>
; __device__ __forceinline__ void gemm_phase(LAS unsigned char* lds, const Gemm g, int G, int cid, const Epi& E) {
;     ...
;             PG8_LDB(B0, 0, 0); PG8_LDB(B1, 0, 1); PG8_SCHED; PG8_LDA(At, 0, 0); PG8_STAGE(PG8_SA(1, 1), a1 + hA, voffA);
;             PG8_WAIT_V(8); PG8_WAIT_L(0); PG8_BAR; PG8_MMA(0, 0, At, B0); PG8_MMA(0, 1, At, B1); PG8_BAR; PG8_SCHED;
;             PG8_LDA(At, 0, 1); PG8_STAGE(PG8_SB(0, 0), b2, voffB); PG8_STAGE(PG8_SB(0, 1), b2 + hB, voffB); PG8_STAGE(PG8_SA(0, 0), a2, voffA);
;             PG8_WAIT_V(8); PG8_WAIT_L(0); PG8_BAR; PG8_MMA(1, 0, At, B0); PG8_MMA(1, 1, At, B1); PG8_BAR; PG8_SCHED;
.LBB0_927:
	s_add_u32 s40, s48, 0x100
	s_addc_u32 s41, s49, 0
	s_add_i32 s6, 0, 0x10000
	s_cmpk_eq_i32 s79, 0x54
	s_cselect_b32 s53, s45, s41
	s_cselect_b32 s52, s44, s40
	s_cselect_b32 s51, s30, s78
	s_cselect_b32 s50, s76, s77
	s_add_i32 s86, 0, 0x14000
	v_add_u32_e32 v144, s6, v243
	v_add_u32_e32 v160, s86, v243
	ds_read_b128 v[128:131], v144
	ds_read_b128 v[132:135], v144 offset:1024
	ds_read_b128 v[140:143], v144 offset:2048
	ds_read_b128 v[144:147], v144 offset:3072
	ds_read_b128 v[148:151], v160
	ds_read_b128 v[152:155], v160 offset:1024
	ds_read_b128 v[156:159], v160 offset:2048
	ds_read_b128 v[160:163], v160 offset:3072
	v_lshl_add_u64 v[198:199], s[48:49], 0, v[210:211]
	s_add_i32 m0, s12, 0xc000
	ds_read_b128 v[164:167], v245
	ds_read_b128 v[168:171], v245 offset:1024
	ds_read_b128 v[172:175], v245 offset:2048
	ds_read_b128 v[176:179], v245 offset:3072
	ds_read_b128 v[180:183], v245 offset:4096
	ds_read_b128 v[184:187], v245 offset:5120
	ds_read_b128 v[188:191], v245 offset:6144
	ds_read_b128 v[214:217], v245 offset:7168
	global_load_lds_dwordx4 v[198:199], off
	v_lshl_add_u64 v[198:199], s[48:49], 0, v[212:213]
	s_add_i32 m0, s12, 0xe000
	s_nop 0
	global_load_lds_dwordx4 v[198:199], off
	s_add_i32 vcc_lo, s79, 2
	s_lshl_b32 vcc_lo, vcc_lo, 15
	s_and_b32 vcc_lo, vcc_lo, 0x1f0000
	s_lshl_b32 vcc_hi, s75, 21
	s_add_i32 vcc_lo, vcc_lo, vcc_hi
	s_lshl_b32 vcc_hi, s25, 3
	s_add_i32 vcc_lo, vcc_lo, vcc_hi
	s_lshl_b32 vcc_hi, s74, 10
	s_add_i32 vcc_lo, vcc_lo, vcc_hi
	s_add_u32 vcc_lo, s82, vcc_lo
	s_addc_u32 vcc_hi, s83, 0
	s_mov_b32 m0, 0x22c00
	s_nop 0
	global_load_lds_dwordx4 v226, vcc
	s_waitcnt vmcnt(9)
	s_waitcnt lgkmcnt(0)
	s_barrier
	s_setprio 1
	v_mfma_f32_16x16x32_bf16 v[124:127], v[128:131], v[164:167], v[124:127]
	v_mfma_f32_16x16x32_bf16 v[120:123], v[140:143], v[164:167], v[120:123]
	v_mfma_f32_16x16x32_bf16 v[108:111], v[128:131], v[172:175], v[108:111]
	v_mfma_f32_16x16x32_bf16 v[104:107], v[140:143], v[172:175], v[104:107]
	v_mfma_f32_16x16x32_bf16 v[92:95], v[128:131], v[180:183], v[92:95]
	v_mfma_f32_16x16x32_bf16 v[88:91], v[140:143], v[180:183], v[88:91]
	v_mfma_f32_16x16x32_bf16 v[76:79], v[128:131], v[188:191], v[76:79]
	v_mfma_f32_16x16x32_bf16 v[72:75], v[140:143], v[188:191], v[72:75]
	v_mfma_f32_16x16x32_bf16 v[124:127], v[132:135], v[168:171], v[124:127]
	v_mfma_f32_16x16x32_bf16 v[120:123], v[144:147], v[168:171], v[120:123]
	v_mfma_f32_16x16x32_bf16 v[108:111], v[132:135], v[176:179], v[108:111]
	v_mfma_f32_16x16x32_bf16 v[104:107], v[144:147], v[176:179], v[104:107]
	v_mfma_f32_16x16x32_bf16 v[92:95], v[132:135], v[184:187], v[92:95]
	v_mfma_f32_16x16x32_bf16 v[88:91], v[144:147], v[184:187], v[88:91]
	v_mfma_f32_16x16x32_bf16 v[76:79], v[132:135], v[214:217], v[76:79]
	v_mfma_f32_16x16x32_bf16 v[72:75], v[144:147], v[214:217], v[72:75]
	s_setprio 0
	s_setprio 1
	v_mfma_f32_16x16x32_bf16 v[116:119], v[148:151], v[164:167], v[116:119]
	v_mfma_f32_16x16x32_bf16 v[112:115], v[156:159], v[164:167], v[112:115]
	v_mfma_f32_16x16x32_bf16 v[100:103], v[148:151], v[172:175], v[100:103]
	v_mfma_f32_16x16x32_bf16 v[96:99], v[156:159], v[172:175], v[96:99]
	v_mfma_f32_16x16x32_bf16 v[84:87], v[148:151], v[180:183], v[84:87]
	v_mfma_f32_16x16x32_bf16 v[80:83], v[156:159], v[180:183], v[80:83]
	v_mfma_f32_16x16x32_bf16 v[68:71], v[148:151], v[188:191], v[68:71]
	v_mfma_f32_16x16x32_bf16 v[64:67], v[156:159], v[188:191], v[64:67]
	v_mfma_f32_16x16x32_bf16 v[116:119], v[152:155], v[168:171], v[116:119]
	v_mfma_f32_16x16x32_bf16 v[112:115], v[160:163], v[168:171], v[112:115]
	v_mfma_f32_16x16x32_bf16 v[100:103], v[152:155], v[176:179], v[100:103]
	v_mfma_f32_16x16x32_bf16 v[96:99], v[160:163], v[176:179], v[96:99]
	v_mfma_f32_16x16x32_bf16 v[84:87], v[152:155], v[184:187], v[84:87]
	v_mfma_f32_16x16x32_bf16 v[80:83], v[160:163], v[184:187], v[80:83]
	v_mfma_f32_16x16x32_bf16 v[68:71], v[152:155], v[214:217], v[68:71]
	v_mfma_f32_16x16x32_bf16 v[64:67], v[160:163], v[214:217], v[64:67]
	s_setprio 0
	s_barrier
	s_add_i32 s6, s6, s25
	v_lshl_add_u64 v[198:199], s[50:51], 0, v[138:139]
	s_mov_b32 m0, s6
	ds_read_b128 v[164:167], v245 offset:16384
	ds_read_b128 v[168:171], v245 offset:17408
	ds_read_b128 v[172:175], v245 offset:18432
	ds_read_b128 v[176:179], v245 offset:19456
	ds_read_b128 v[180:183], v245 offset:20480
	ds_read_b128 v[184:187], v245 offset:21504
	ds_read_b128 v[188:191], v245 offset:22528
	ds_read_b128 v[214:217], v245 offset:23552
	global_load_lds_dwordx4 v[198:199], off
	s_add_i32 m0, s6, 0x2000
	s_add_u32 s6, s50, 0x2000
	v_lshl_add_u64 v[198:199], s[50:51], 0, v[136:137]
	s_addc_u32 s7, s51, 0
	s_add_i32 s48, s86, s25
	global_load_lds_dwordx4 v[198:199], off
	v_lshl_add_u64 v[198:199], s[6:7], 0, v[138:139]
	s_mov_b32 m0, s48
	v_lshl_add_u64 v[200:201], s[52:53], 0, v[206:207]
	global_load_lds_dwordx4 v[198:199], off
	v_lshl_add_u64 v[198:199], s[6:7], 0, v[136:137]
	s_add_i32 m0, s48, 0x2000
	s_nop 0
	global_load_lds_dwordx4 v[198:199], off
	v_lshl_add_u64 v[198:199], s[52:53], 0, v[208:209]
	s_mov_b32 m0, s12
	s_nop 0
	global_load_lds_dwordx4 v[198:199], off
	s_mov_b32 m0, s13
	s_nop 0
	global_load_lds_dwordx4 v[200:201], off
	s_waitcnt vmcnt(9)
	s_waitcnt lgkmcnt(0)
	s_barrier
; #define PG8_STAGE(bufoff, gbase, voff) do { _Pragma("unroll") for (int _i = 0; _i < 2; ++_i) \
;         __builtin_amdgcn_global_load_lds((const unsigned*)((const char*)(gbase) + (voff)[_i]), (LAS unsigned*)(lds + (bufoff) + ldsw + _i * 8192), 16, 0, 0); } while (0)
; #define PG8_LDA(dst, b, h) do { _Pragma("unroll") for (int m = 0; m < 4; ++m) _Pragma("unroll") for (int k = 0; k < 2; ++k) dst[m][k] = *(const LAS bf16x8*)(lds + PG8_SA(b, h) + aoff + m * 2048 + k * 1024); } while (0)
; #define PG8_LDB(dst, b, h) do { _Pragma("unroll") for (int n = 0; n < 2; ++n) _Pragma("unroll") for (int k = 0; k < 2; ++k) dst[n][k] = *(const LAS bf16x8*)(lds + PG8_SB(b, h) + boff + n * 2048 + k * 1024); } while (0)
; #define PG8_MMA(ai, bj, At, Bt) do { __builtin_amdgcn_s_setprio(1); _Pragma("unroll") for (int m = 0; m < 4; ++m) _Pragma("unroll") for (int n = 0; n < 2; ++n) _Pragma("unroll") for (int k = 0; k < 2; ++k) \
;         acc[ai][bj][m][n] = __builtin_amdgcn_mfma_f32_16x16x32_bf16(Bt[n][k], At[m][k], acc[ai][bj][m][n], 0, 0, 0); __builtin_amdgcn_s_setprio(0); } while (0)
; #define PG8_WAIT_V(n) asm volatile("s_waitcnt vmcnt(" #n ")" ::: "memory")
; #define PG8_WAIT_L(n) asm volatile("s_waitcnt lgkmcnt(" #n ")" ::: "memory")
; #define PG8_BAR __builtin_amdgcn_s_barrier()
; #define PG8_SCHED __builtin_amdgcn_sched_barrier(0)
; template <class Epi, bool ALIGN_EPI>
; __device__ __forceinline__ void gemm_phase(LAS unsigned char* lds, const Gemm g, int G, int cid, const Epi& E) {
;     ...
;             PG8_WAIT_V(8); PG8_WAIT_L(0); PG8_BAR; PG8_MMA(1, 0, At, B0); PG8_MMA(1, 1, At, B1); PG8_BAR; PG8_SCHED;
;             PG8_LDB(B0, 1, 0); PG8_LDB(B1, 1, 1); PG8_SCHED; PG8_LDA(At, 1, 0); PG8_STAGE(PG8_SA(0, 1), a2 + hA, voffA);
;             PG8_WAIT_V(8); PG8_WAIT_L(0); PG8_BAR; PG8_MMA(0, 0, At, B0); PG8_MMA(0, 1, At, B1); PG8_BAR; PG8_SCHED;
	s_setprio 1
	v_mfma_f32_16x16x32_bf16 v[60:63], v[128:131], v[164:167], v[60:63]
	v_mfma_f32_16x16x32_bf16 v[56:59], v[140:143], v[164:167], v[56:59]
	v_mfma_f32_16x16x32_bf16 v[44:47], v[128:131], v[172:175], v[44:47]
	v_mfma_f32_16x16x32_bf16 v[40:43], v[140:143], v[172:175], v[40:43]
	v_mfma_f32_16x16x32_bf16 v[28:31], v[128:131], v[180:183], v[28:31]
	v_mfma_f32_16x16x32_bf16 v[24:27], v[140:143], v[180:183], v[24:27]
	v_mfma_f32_16x16x32_bf16 v[12:15], v[128:131], v[188:191], v[12:15]
	v_mfma_f32_16x16x32_bf16 v[8:11], v[140:143], v[188:191], v[8:11]
	v_mfma_f32_16x16x32_bf16 v[60:63], v[132:135], v[168:171], v[60:63]
	v_mfma_f32_16x16x32_bf16 v[56:59], v[144:147], v[168:171], v[56:59]
	v_mfma_f32_16x16x32_bf16 v[44:47], v[132:135], v[176:179], v[44:47]
	v_mfma_f32_16x16x32_bf16 v[40:43], v[144:147], v[176:179], v[40:43]
	v_mfma_f32_16x16x32_bf16 v[28:31], v[132:135], v[184:187], v[28:31]
	v_mfma_f32_16x16x32_bf16 v[24:27], v[144:147], v[184:187], v[24:27]
	v_mfma_f32_16x16x32_bf16 v[12:15], v[132:135], v[214:217], v[12:15]
	v_mfma_f32_16x16x32_bf16 v[8:11], v[144:147], v[214:217], v[8:11]
	s_setprio 0
	s_setprio 1
	v_mfma_f32_16x16x32_bf16 v[52:55], v[148:151], v[164:167], v[52:55]
	v_mfma_f32_16x16x32_bf16 v[48:51], v[156:159], v[164:167], v[48:51]
	v_mfma_f32_16x16x32_bf16 v[36:39], v[148:151], v[172:175], v[36:39]
	v_mfma_f32_16x16x32_bf16 v[32:35], v[156:159], v[172:175], v[32:35]
	v_mfma_f32_16x16x32_bf16 v[20:23], v[148:151], v[180:183], v[20:23]
	v_mfma_f32_16x16x32_bf16 v[16:19], v[156:159], v[180:183], v[16:19]
	v_mfma_f32_16x16x32_bf16 v[4:7], v[148:151], v[188:191], v[4:7]
	v_mfma_f32_16x16x32_bf16 v[0:3], v[156:159], v[188:191], v[0:3]
	v_mfma_f32_16x16x32_bf16 v[52:55], v[152:155], v[168:171], v[52:55]
	v_mfma_f32_16x16x32_bf16 v[48:51], v[160:163], v[168:171], v[48:51]
	v_mfma_f32_16x16x32_bf16 v[36:39], v[152:155], v[176:179], v[36:39]
	v_mfma_f32_16x16x32_bf16 v[32:35], v[160:163], v[176:179], v[32:35]
	v_mfma_f32_16x16x32_bf16 v[20:23], v[152:155], v[184:187], v[20:23]
	v_mfma_f32_16x16x32_bf16 v[16:19], v[160:163], v[184:187], v[16:19]
	v_mfma_f32_16x16x32_bf16 v[4:7], v[152:155], v[214:217], v[4:7]
	v_mfma_f32_16x16x32_bf16 v[0:3], v[160:163], v[214:217], v[0:3]
	s_setprio 0
	s_barrier
	s_add_i32 s48, 0, 0x18000
	s_add_i32 s49, 0, 0x1c000
	v_add_u32_e32 v144, s48, v243
	v_add_u32_e32 v160, s49, v243
	ds_read_b128 v[128:131], v144
	ds_read_b128 v[132:135], v144 offset:1024
	ds_read_b128 v[140:143], v144 offset:2048
	ds_read_b128 v[144:147], v144 offset:3072
	ds_read_b128 v[148:151], v160
	ds_read_b128 v[152:155], v160 offset:1024
	ds_read_b128 v[156:159], v160 offset:2048
	ds_read_b128 v[160:163], v160 offset:3072
	s_add_u32 s6, s52, 0x160000
	s_addc_u32 s7, s53, 0
	s_mov_b32 m0, s54
	v_lshl_add_u64 v[218:219], s[6:7], 0, v[208:209]
	ds_read_b128 v[164:167], v245 offset:32768
	ds_read_b128 v[168:171], v245 offset:33792
	ds_read_b128 v[172:175], v245 offset:34816
	ds_read_b128 v[176:179], v245 offset:35840
	ds_read_b128 v[180:183], v245 offset:36864
	ds_read_b128 v[184:187], v245 offset:37888
	ds_read_b128 v[188:191], v245 offset:38912
	ds_read_b128 v[214:217], v245 offset:39936
	global_load_lds_dwordx4 v[218:219], off
	v_lshl_add_u64 v[218:219], s[6:7], 0, v[206:207]
	s_mov_b32 m0, s55
	s_nop 0
	global_load_lds_dwordx4 v[218:219], off
	s_waitcnt vmcnt(8)
	s_waitcnt lgkmcnt(0)
	s_barrier
	s_setprio 1
	v_mfma_f32_16x16x32_bf16 v[124:127], v[128:131], v[164:167], v[124:127]
	v_mfma_f32_16x16x32_bf16 v[120:123], v[140:143], v[164:167], v[120:123]
	v_mfma_f32_16x16x32_bf16 v[108:111], v[128:131], v[172:175], v[108:111]
	v_mfma_f32_16x16x32_bf16 v[104:107], v[140:143], v[172:175], v[104:107]
	v_mfma_f32_16x16x32_bf16 v[92:95], v[128:131], v[180:183], v[92:95]
	v_mfma_f32_16x16x32_bf16 v[88:91], v[140:143], v[180:183], v[88:91]
	v_mfma_f32_16x16x32_bf16 v[76:79], v[128:131], v[188:191], v[76:79]
	v_mfma_f32_16x16x32_bf16 v[72:75], v[140:143], v[188:191], v[72:75]
	v_mfma_f32_16x16x32_bf16 v[124:127], v[132:135], v[168:171], v[124:127]
	v_mfma_f32_16x16x32_bf16 v[120:123], v[144:147], v[168:171], v[120:123]
	v_mfma_f32_16x16x32_bf16 v[108:111], v[132:135], v[176:179], v[108:111]
	v_mfma_f32_16x16x32_bf16 v[104:107], v[144:147], v[176:179], v[104:107]
	v_mfma_f32_16x16x32_bf16 v[92:95], v[132:135], v[184:187], v[92:95]
	v_mfma_f32_16x16x32_bf16 v[88:91], v[144:147], v[184:187], v[88:91]
	v_mfma_f32_16x16x32_bf16 v[76:79], v[132:135], v[214:217], v[76:79]
	v_mfma_f32_16x16x32_bf16 v[72:75], v[144:147], v[214:217], v[72:75]
	s_setprio 0
	s_setprio 1
	v_mfma_f32_16x16x32_bf16 v[116:119], v[148:151], v[164:167], v[116:119]
	v_mfma_f32_16x16x32_bf16 v[112:115], v[156:159], v[164:167], v[112:115]
	v_mfma_f32_16x16x32_bf16 v[100:103], v[148:151], v[172:175], v[100:103]
	v_mfma_f32_16x16x32_bf16 v[96:99], v[156:159], v[172:175], v[96:99]
	v_mfma_f32_16x16x32_bf16 v[84:87], v[148:151], v[180:183], v[84:87]
	v_mfma_f32_16x16x32_bf16 v[80:83], v[156:159], v[180:183], v[80:83]
	v_mfma_f32_16x16x32_bf16 v[68:71], v[148:151], v[188:191], v[68:71]
	v_mfma_f32_16x16x32_bf16 v[64:67], v[156:159], v[188:191], v[64:67]
	v_mfma_f32_16x16x32_bf16 v[116:119], v[152:155], v[168:171], v[116:119]
	v_mfma_f32_16x16x32_bf16 v[112:115], v[160:163], v[168:171], v[112:115]
	v_mfma_f32_16x16x32_bf16 v[100:103], v[152:155], v[176:179], v[100:103]
	v_mfma_f32_16x16x32_bf16 v[96:99], v[160:163], v[176:179], v[96:99]
	v_mfma_f32_16x16x32_bf16 v[84:87], v[152:155], v[184:187], v[84:87]
	v_mfma_f32_16x16x32_bf16 v[80:83], v[160:163], v[184:187], v[80:83]
	v_mfma_f32_16x16x32_bf16 v[68:71], v[152:155], v[214:217], v[68:71]
	v_mfma_f32_16x16x32_bf16 v[64:67], v[160:163], v[214:217], v[64:67]
	s_setprio 0
	s_barrier
; #define PG8_STAGE(bufoff, gbase, voff) do { _Pragma("unroll") for (int _i = 0; _i < 2; ++_i) \
;         __builtin_amdgcn_global_load_lds((const unsigned*)((const char*)(gbase) + (voff)[_i]), (LAS unsigned*)(lds + (bufoff) + ldsw + _i * 8192), 16, 0, 0); } while (0)
; #define PG8_LDA(dst, b, h) do { _Pragma("unroll") for (int m = 0; m < 4; ++m) _Pragma("unroll") for (int k = 0; k < 2; ++k) dst[m][k] = *(const LAS bf16x8*)(lds + PG8_SA(b, h) + aoff + m * 2048 + k * 1024); } while (0)
; #define PG8_WAIT_V(n) asm volatile("s_waitcnt vmcnt(" #n ")" ::: "memory")
; #define PG8_WAIT_L(n) asm volatile("s_waitcnt lgkmcnt(" #n ")" ::: "memory")
; #define PG8_BAR __builtin_amdgcn_s_barrier()
; template <class Epi, bool ALIGN_EPI>
; __device__ __forceinline__ void gemm_phase(LAS unsigned char* lds, const Gemm g, int G, int cid, const Epi& E) {
;     ...
;             PG8_LDA(At, 1, 1); PG8_STAGE(PG8_SB(1, 0), b3, voffB); PG8_STAGE(PG8_SB(1, 1), b3 + hB, voffB); PG8_STAGE(PG8_SA(1, 0), a3, voffA);
;             PG8_WAIT_V(8); PG8_WAIT_L(0); PG8_BAR; PG8_MMA(1, 0, At, B0); PG8_MMA(1, 1, At, B1); PG8_BAR; PG8_SCHED;
;         }
;     __device__ __forceinline__ void operator()(const f32x4 (&acc)[2][2][4][2], const Unit& u, int wr, int wc, int fr, int fq, const LAS float*) const {
;     ...
;         for (int am = 0; am < NB; ++am) { const int ai = am / (NB / 2), m0 = (am % (NB / 2)) * MB;
;             f32x4 xo[4][2][2];
; #pragma unroll
;             for (int m = m0; m < m0 + MB; ++m) { const float* xr = Xs + (size_t)(row0 + ai * HALF + m * 16) * DM + col0;
; #pragma unroll
;                 for (int bj = 0; bj < 2; ++bj) { xo[m][bj][0] = *(const f32x4*)(xr + bj * HALF); xo[m][bj][1] = *(const f32x4*)(xr + bj * HALF + 4); } }
; #pragma unroll
;             for (int m = m0; m < m0 + MB; ++m) { const int row = row0 + ai * HALF + m * 16; float ss = 0.f;
;                 float* xr = X + (size_t)row * DM + col0; bf16_t* xb = XB + (size_t)row * ALD + col0;
; #pragma unroll
;                 for (int bj = 0; bj < 2; ++bj) { f32x4 x0 = xo[m][bj][0], x1 = xo[m][bj][1];
;                     if (HB) { x0 += (acc[ai][bj][m][0] + bv[bj][0]) * sv[bj][0]; x1 += (acc[ai][bj][m][1] + bv[bj][1]) * sv[bj][1]; } else { x0 += acc[ai][bj][m][0]; x1 += acc[ai][bj][m][1]; }
;                     *(f32x4*)(xr + bj * HALF) = x0; *(f32x4*)(xr + bj * HALF + 4) = x1;
	s_add_u32 s6, s50, 0x40000
	s_addc_u32 s7, s51, 0
	s_add_i32 s48, s48, s25
	v_lshl_add_u64 v[218:219], s[6:7], 0, v[138:139]
	s_mov_b32 m0, s48
	ds_read_b128 v[164:167], v245 offset:49152
	ds_read_b128 v[168:171], v245 offset:50176
	ds_read_b128 v[172:175], v245 offset:51200
	ds_read_b128 v[176:179], v245 offset:52224
	ds_read_b128 v[180:183], v245 offset:53248
	ds_read_b128 v[184:187], v245 offset:54272
	ds_read_b128 v[188:191], v245 offset:55296
	ds_read_b128 v[214:217], v245 offset:56320
	global_load_lds_dwordx4 v[218:219], off
	s_add_i32 m0, s48, 0x2000
	v_lshl_add_u64 v[218:219], s[6:7], 0, v[136:137]
	s_add_u32 s6, s50, 0x42000
	s_addc_u32 s7, s51, 0
	s_add_i32 s48, s49, s25
	global_load_lds_dwordx4 v[218:219], off
	v_lshl_add_u64 v[218:219], s[6:7], 0, v[138:139]
	s_mov_b32 m0, s48
	v_lshl_add_u64 v[198:199], v[198:199], 0, s[36:37]
	global_load_lds_dwordx4 v[218:219], off
	v_lshl_add_u64 v[218:219], s[6:7], 0, v[136:137]
	s_add_i32 m0, s48, 0x2000
	s_nop 0
	global_load_lds_dwordx4 v[218:219], off
	s_mov_b32 m0, s57
	s_nop 0
	global_load_lds_dwordx4 v[198:199], off
	v_lshl_add_u64 v[198:199], v[200:201], 0, s[36:37]
	s_mov_b32 m0, s58
	s_nop 0
	global_load_lds_dwordx4 v[198:199], off
	s_waitcnt vmcnt(8)
	s_waitcnt lgkmcnt(0)
	s_barrier
	s_setprio 1
	v_mfma_f32_16x16x32_bf16 v[60:63], v[128:131], v[164:167], v[60:63]
	v_mfma_f32_16x16x32_bf16 v[56:59], v[140:143], v[164:167], v[56:59]
	v_mfma_f32_16x16x32_bf16 v[44:47], v[128:131], v[172:175], v[44:47]
	v_mfma_f32_16x16x32_bf16 v[40:43], v[140:143], v[172:175], v[40:43]
	v_mfma_f32_16x16x32_bf16 v[28:31], v[128:131], v[180:183], v[28:31]
	v_mfma_f32_16x16x32_bf16 v[24:27], v[140:143], v[180:183], v[24:27]
	v_mfma_f32_16x16x32_bf16 v[12:15], v[128:131], v[188:191], v[12:15]
	v_mfma_f32_16x16x32_bf16 v[8:11], v[140:143], v[188:191], v[8:11]
	v_mfma_f32_16x16x32_bf16 v[60:63], v[132:135], v[168:171], v[60:63]
	v_mfma_f32_16x16x32_bf16 v[56:59], v[144:147], v[168:171], v[56:59]
	v_mfma_f32_16x16x32_bf16 v[44:47], v[132:135], v[176:179], v[44:47]
	v_mfma_f32_16x16x32_bf16 v[40:43], v[144:147], v[176:179], v[40:43]
	v_mfma_f32_16x16x32_bf16 v[28:31], v[132:135], v[184:187], v[28:31]
	v_mfma_f32_16x16x32_bf16 v[24:27], v[144:147], v[184:187], v[24:27]
	v_mfma_f32_16x16x32_bf16 v[12:15], v[132:135], v[214:217], v[12:15]
	v_mfma_f32_16x16x32_bf16 v[8:11], v[144:147], v[214:217], v[8:11]
	s_setprio 0
	s_setprio 1
	v_mfma_f32_16x16x32_bf16 v[52:55], v[148:151], v[164:167], v[52:55]
	v_mfma_f32_16x16x32_bf16 v[48:51], v[156:159], v[164:167], v[48:51]
	v_mfma_f32_16x16x32_bf16 v[36:39], v[148:151], v[172:175], v[36:39]
	v_mfma_f32_16x16x32_bf16 v[32:35], v[156:159], v[172:175], v[32:35]
	v_mfma_f32_16x16x32_bf16 v[20:23], v[148:151], v[180:183], v[20:23]
	v_mfma_f32_16x16x32_bf16 v[16:19], v[156:159], v[180:183], v[16:19]
	v_mfma_f32_16x16x32_bf16 v[4:7], v[148:151], v[188:191], v[4:7]
	v_mfma_f32_16x16x32_bf16 v[0:3], v[156:159], v[188:191], v[0:3]
	v_mfma_f32_16x16x32_bf16 v[52:55], v[152:155], v[168:171], v[52:55]
	v_mfma_f32_16x16x32_bf16 v[48:51], v[160:163], v[168:171], v[48:51]
	v_mfma_f32_16x16x32_bf16 v[36:39], v[152:155], v[176:179], v[36:39]
	v_mfma_f32_16x16x32_bf16 v[32:35], v[160:163], v[176:179], v[32:35]
	v_mfma_f32_16x16x32_bf16 v[20:23], v[152:155], v[184:187], v[20:23]
	v_mfma_f32_16x16x32_bf16 v[16:19], v[160:163], v[184:187], v[16:19]
	v_mfma_f32_16x16x32_bf16 v[4:7], v[152:155], v[214:217], v[4:7]
	v_mfma_f32_16x16x32_bf16 v[0:3], v[160:163], v[214:217], v[0:3]
	s_setprio 0
	s_barrier
	s_add_i32 s79, s79, 2
	s_add_u32 s77, s77, 0x80000
	s_addc_u32 s78, s78, 0
	s_cmpk_gt_u32 s79, 0x55
	s_mov_b64 s[48:49], s[40:41]
	s_cbranch_scc0 .LBB0_927
	v_lshl_or_b32 v214, s74, 8, v244
	v_lshl_add_u32 v216, s75, 8, v197
	v_ashrrev_i32_e32 v215, 31, v214
	v_lshlrev_b64 v[198:199], 2, v[214:215]
	v_ashrrev_i32_e32 v217, 31, v216
	v_or_b32_e32 v226, 16, v216
	v_lshl_add_u64 v[218:219], s[82:83], 0, v[198:199]
	v_lshlrev_b64 v[200:201], 13, v[216:217]
	v_ashrrev_i32_e32 v227, 31, v226
	v_or_b32_e32 v222, 32, v216
	v_or_b32_e32 v220, 48, v216
	v_lshl_add_u64 v[128:129], v[218:219], 0, v[200:201]
	v_lshlrev_b64 v[230:231], 13, v[226:227]
	v_ashrrev_i32_e32 v223, 31, v222
	v_ashrrev_i32_e32 v221, 31, v220
	global_load_dwordx4 v[188:191], v[128:129], off offset:16
	global_load_dwordx4 v[246:249], v[128:129], off
	global_load_dwordx4 v[180:183], v[128:129], off offset:528
	global_load_dwordx4 v[184:187], v[128:129], off offset:512
	v_lshl_add_u64 v[128:129], v[218:219], 0, v[230:231]
	v_lshlrev_b64 v[228:229], 13, v[222:223]
	v_lshlrev_b64 v[224:225], 13, v[220:221]
	global_load_dwordx4 v[172:175], v[128:129], off offset:16
	global_load_dwordx4 v[176:179], v[128:129], off
	global_load_dwordx4 v[164:167], v[128:129], off offset:528
	global_load_dwordx4 v[168:171], v[128:129], off offset:512
	v_lshl_add_u64 v[128:129], v[218:219], 0, v[228:229]
	v_lshl_add_u64 v[132:133], v[218:219], 0, v[224:225]
	global_load_dwordx4 v[156:159], v[128:129], off offset:16
	global_load_dwordx4 v[160:163], v[128:129], off
	global_load_dwordx4 v[148:151], v[128:129], off offset:528
	global_load_dwordx4 v[152:155], v[128:129], off offset:512
	global_load_dwordx4 v[140:143], v[132:133], off offset:16
	global_load_dwordx4 v[144:147], v[132:133], off
	s_nop 0
	global_load_dwordx4 v[128:131], v[132:133], off offset:528
	s_nop 0
	global_load_dwordx4 v[132:135], v[132:133], off offset:512
	v_lshl_add_u64 v[200:201], s[82:83], 0, v[200:201]
	v_lshl_add_u64 v[234:235], v[200:201], 0, v[198:199]
	v_mov_b64_e32 v[198:199], s[4:5]
	v_mad_i64_i32 v[198:199], s[6:7], v216, s66, v[198:199]
	v_lshl_add_u64 v[232:233], v[214:215], 1, v[198:199]
	s_and_b64 vcc, exec, s[28:29]
	s_waitcnt vmcnt(12)
	v_pk_add_f32 v[122:123], v[122:123], v[190:191]
	v_pk_add_f32 v[126:127], v[126:127], v[248:249]
	v_pk_add_f32 v[124:125], v[124:125], v[246:247]
	v_pk_add_f32 v[120:121], v[120:121], v[188:189]
	global_store_dwordx4 v[234:235], v[124:127], off
	global_store_dwordx4 v[234:235], v[120:123], off offset:16
	v_cvt_pk_bf16_f32 v188, v124, v125
	v_cvt_pk_bf16_f32 v189, v126, v127
	v_cvt_pk_bf16_f32 v190, v120, v121
	v_cvt_pk_bf16_f32 v191, v122, v123
	s_cbranch_vccz .LBB0_930
	global_store_dwordx4 v[232:233], v[188:191], off
